# plus FFN-up epilogue: 192 register copies fused into their full-row DPP rotates
# speedup vs baseline: 1.0310x; 1.0031x over previous
; #define LAS __attribute__((address_space(3)))
;     template <int M_> __device__ __forceinline__ f32x4 conv4(const f32x4 c4, const f32x4 pg, const LAS float* bp, int fr, const f32x4 w0, const f32x4 w1, const f32x4 w2, const f32x4 bsv, int db) const {
;         f32x4 p1, p2;
;         if (M_ > 0) {
; #pragma unroll
;             for (int e = 0; e < 4; ++e) { p1[e] = dpp_f<0x111>(dpp_r<0x121>(pg[e]), c4[e]); p2[e] = dpp_f<0x112>(dpp_r<0x122>(pg[e]), c4[e]); }
;         } else {
;             const f32x4 x1 = *(const LAS f32x4*)(bp + 256), x2 = *(const LAS f32x4*)(bp + (fr & 1) * 256);
; #pragma unroll
;             for (int e = 0; e < 4; ++e) { p1[e] = dpp_f<0x111>(x1[e], c4[e]); p2[e] = dpp_f<0x112>(x2[e], c4[e]); }
;         }
;         if ((unsigned)(db + 1) < 17u) { const int d = fr - db;
; #pragma unroll
;             for (int e = 0; e < 4; ++e) { p1[e] = d == 0 ? 0.f : p1[e]; p2[e] = (unsigned)d < 2u ? 0.f : p2[e]; } }
;         f32x4 uu = bsv + w2 * c4 + w1 * p1 + w0 * p2;
;         asm volatile("" : "+v"(uu));
;         return uu;
;     }
;     __device__ __forceinline__ void prompt(f32x4 (&acc)[2][2][4][2], const Unit& u, int row0t, int wr, int wc, int fr, int fq) const {
;     ...
;         for (int n = 0; n < 2; ++n) {
;             const unsigned cso = (unsigned)((ca + 4 * n) * 4);
;             const f32x4 w0 = *(const f32x4*)((const char*)cw + cso), w1 = *(const f32x4*)((const char*)(cw + DFF2) + cso), w2 = *(const f32x4*)((const char*)(cw + 2 * DFF2) + cso), bsv = *(const f32x4*)((const char*)cb + cso);
; #pragma unroll
;             for (int ai = 0; ai < 2; ++ai) {
;                 int ps = ai * 2 + wr - 1; ps = ps < 0 ? 0 : ps;
;                 const LAS float* bp = bnd + (ps * 2) * 256 + cl + 4 * n;
;                 const int db0 = rho_b - (ai * HALF + wr * 64);
;                 acc[ai][0][3][n] = conv4<3>(acc[ai][0][3][n], acc[ai][0][2][n], bp, fr, w0, w1, w2, bsv, db0 - 48);
;                 acc[ai][0][2][n] = conv4<2>(acc[ai][0][2][n], acc[ai][0][1][n], bp, fr, w0, w1, w2, bsv, db0 - 32);
;                 acc[ai][0][1][n] = conv4<1>(acc[ai][0][1][n], acc[ai][0][0][n], bp, fr, w0, w1, w2, bsv, db0 - 16);
;                 acc[ai][0][0][n] = conv4<0>(acc[ai][0][0][n], acc[ai][0][0][n], bp, fr, w0, w1, w2, bsv, db0);
;             }
.LBB0_1161:
	v_lshlrev_b32_e32 v175, 2, v174
	global_load_dwordx4 v[148:151], v175, s[54:55]
	global_load_dwordx4 v[156:159], v175, s[34:35]
	global_load_dwordx4 v[24:27], v175, s[96:97]
	global_load_dwordx4 v[160:163], v175, s[66:67]
	s_sub_i32 s2, s8, s86
	s_sub_i32 s0, s2, 47
	v_mov_b32_dpp v38, v168 row_ror:1 row_mask:0xf bank_mask:0xf
	v_mov_b32_dpp v36, v168 row_ror:2 row_mask:0xf bank_mask:0xf
	v_mov_b32_dpp v39, v169 row_ror:1 row_mask:0xf bank_mask:0xf
	v_mov_b32_dpp v37, v169 row_ror:2 row_mask:0xf bank_mask:0xf
	v_mov_b32_dpp v54, v170 row_ror:1 row_mask:0xf bank_mask:0xf
	v_mov_b32_dpp v52, v170 row_ror:2 row_mask:0xf bank_mask:0xf
	v_mov_b32_dpp v55, v171 row_ror:1 row_mask:0xf bank_mask:0xf
	v_mov_b32_dpp v53, v171 row_ror:2 row_mask:0xf bank_mask:0xf
	s_cmp_gt_u32 s0, 16
	v_mov_b32_dpp v38, v152 row_shr:1 row_mask:0xf bank_mask:0xf
	v_mov_b32_dpp v36, v152 row_shr:2 row_mask:0xf bank_mask:0xf
	v_mov_b32_dpp v39, v153 row_shr:1 row_mask:0xf bank_mask:0xf
	v_mov_b32_dpp v37, v153 row_shr:2 row_mask:0xf bank_mask:0xf
	v_mov_b32_dpp v54, v154 row_shr:1 row_mask:0xf bank_mask:0xf
	v_mov_b32_dpp v52, v154 row_shr:2 row_mask:0xf bank_mask:0xf
	v_mov_b32_dpp v55, v155 row_shr:1 row_mask:0xf bank_mask:0xf
	v_mov_b32_dpp v53, v155 row_shr:2 row_mask:0xf bank_mask:0xf
	s_cselect_b64 s[6:7], -1, 0
	s_cmp_lt_u32 s0, 17
	s_mov_b64 s[0:1], -1
	s_cbranch_scc1 .LBB0_1163
	s_mov_b64 s[0:1], 0

; #define LAS __attribute__((address_space(3)))
;     template <int M_> __device__ __forceinline__ f32x4 conv4(const f32x4 c4, const f32x4 pg, const LAS float* bp, int fr, const f32x4 w0, const f32x4 w1, const f32x4 w2, const f32x4 bsv, int db) const {
;         f32x4 p1, p2;
;         if (M_ > 0) {
; #pragma unroll
;             for (int e = 0; e < 4; ++e) { p1[e] = dpp_f<0x111>(dpp_r<0x121>(pg[e]), c4[e]); p2[e] = dpp_f<0x112>(dpp_r<0x122>(pg[e]), c4[e]); }
;         } else {
;             const f32x4 x1 = *(const LAS f32x4*)(bp + 256), x2 = *(const LAS f32x4*)(bp + (fr & 1) * 256);
; #pragma unroll
;             for (int e = 0; e < 4; ++e) { p1[e] = dpp_f<0x111>(x1[e], c4[e]); p2[e] = dpp_f<0x112>(x2[e], c4[e]); }
;         }
;         if ((unsigned)(db + 1) < 17u) { const int d = fr - db;
; #pragma unroll
;             for (int e = 0; e < 4; ++e) { p1[e] = d == 0 ? 0.f : p1[e]; p2[e] = (unsigned)d < 2u ? 0.f : p2[e]; } }
;         f32x4 uu = bsv + w2 * c4 + w1 * p1 + w0 * p2;
;         asm volatile("" : "+v"(uu));
;         return uu;
;     }
;     __device__ __forceinline__ void prompt(f32x4 (&acc)[2][2][4][2], const Unit& u, int row0t, int wr, int wc, int fr, int fq) const {
;     ...
;                 const int db0 = rho_b - (ai * HALF + wr * 64);
;                 acc[ai][0][3][n] = conv4<3>(acc[ai][0][3][n], acc[ai][0][2][n], bp, fr, w0, w1, w2, bsv, db0 - 48);
;                 acc[ai][0][2][n] = conv4<2>(acc[ai][0][2][n], acc[ai][0][1][n], bp, fr, w0, w1, w2, bsv, db0 - 32);
;                 acc[ai][0][1][n] = conv4<1>(acc[ai][0][1][n], acc[ai][0][0][n], bp, fr, w0, w1, w2, bsv, db0 - 16);
;                 acc[ai][0][0][n] = conv4<0>(acc[ai][0][0][n], acc[ai][0][0][n], bp, fr, w0, w1, w2, bsv, db0);
.LBB0_1165:
	s_waitcnt vmcnt(0)
	v_pk_fma_f32 v[76:77], v[154:155], v[158:159], v[162:163]
	v_pk_fma_f32 v[78:79], v[152:153], v[156:157], v[160:161]
	v_pk_fma_f32 v[54:55], v[150:151], v[54:55], v[76:77]
	v_pk_fma_f32 v[38:39], v[148:149], v[38:39], v[78:79]
	v_pk_fma_f32 v[114:115], v[26:27], v[52:53], v[54:55]
	v_pk_fma_f32 v[112:113], v[24:25], v[36:37], v[38:39]
	s_sub_i32 s0, s2, 31
	v_mov_b32_dpp v38, v164 row_ror:1 row_mask:0xf bank_mask:0xf
	v_mov_b32_dpp v36, v164 row_ror:2 row_mask:0xf bank_mask:0xf
	v_mov_b32_dpp v39, v165 row_ror:1 row_mask:0xf bank_mask:0xf
	v_mov_b32_dpp v37, v165 row_ror:2 row_mask:0xf bank_mask:0xf
	v_mov_b32_dpp v54, v166 row_ror:1 row_mask:0xf bank_mask:0xf
	v_mov_b32_dpp v52, v166 row_ror:2 row_mask:0xf bank_mask:0xf
	v_mov_b32_dpp v55, v167 row_ror:1 row_mask:0xf bank_mask:0xf
	v_mov_b32_dpp v53, v167 row_ror:2 row_mask:0xf bank_mask:0xf
	s_cmp_gt_u32 s0, 16
	v_mov_b32_dpp v38, v168 row_shr:1 row_mask:0xf bank_mask:0xf
	v_mov_b32_dpp v36, v168 row_shr:2 row_mask:0xf bank_mask:0xf
	v_mov_b32_dpp v39, v169 row_shr:1 row_mask:0xf bank_mask:0xf
	v_mov_b32_dpp v37, v169 row_shr:2 row_mask:0xf bank_mask:0xf
	v_mov_b32_dpp v54, v170 row_shr:1 row_mask:0xf bank_mask:0xf
	v_mov_b32_dpp v52, v170 row_shr:2 row_mask:0xf bank_mask:0xf
	v_mov_b32_dpp v55, v171 row_shr:1 row_mask:0xf bank_mask:0xf
	v_mov_b32_dpp v53, v171 row_shr:2 row_mask:0xf bank_mask:0xf
	s_cselect_b64 s[8:9], -1, 0
	s_cmp_lt_u32 s0, 17
	s_mov_b64 s[0:1], -1
	s_cbranch_scc1 .LBB0_1167
	s_mov_b64 s[0:1], 0

; #define LAS __attribute__((address_space(3)))
;     template <int M_> __device__ __forceinline__ f32x4 conv4(const f32x4 c4, const f32x4 pg, const LAS float* bp, int fr, const f32x4 w0, const f32x4 w1, const f32x4 w2, const f32x4 bsv, int db) const {
;         f32x4 p1, p2;
;         if (M_ > 0) {
; #pragma unroll
;             for (int e = 0; e < 4; ++e) { p1[e] = dpp_f<0x111>(dpp_r<0x121>(pg[e]), c4[e]); p2[e] = dpp_f<0x112>(dpp_r<0x122>(pg[e]), c4[e]); }
;         } else {
;             const f32x4 x1 = *(const LAS f32x4*)(bp + 256), x2 = *(const LAS f32x4*)(bp + (fr & 1) * 256);
; #pragma unroll
;             for (int e = 0; e < 4; ++e) { p1[e] = dpp_f<0x111>(x1[e], c4[e]); p2[e] = dpp_f<0x112>(x2[e], c4[e]); }
;         }
;         if ((unsigned)(db + 1) < 17u) { const int d = fr - db;
; #pragma unroll
;             for (int e = 0; e < 4; ++e) { p1[e] = d == 0 ? 0.f : p1[e]; p2[e] = (unsigned)d < 2u ? 0.f : p2[e]; } }
;         f32x4 uu = bsv + w2 * c4 + w1 * p1 + w0 * p2;
;         asm volatile("" : "+v"(uu));
;         return uu;
;     }
;     __device__ __forceinline__ void prompt(f32x4 (&acc)[2][2][4][2], const Unit& u, int row0t, int wr, int wc, int fr, int fq) const {
;     ...
;                 const int db0 = rho_b - (ai * HALF + wr * 64);
;                 acc[ai][0][3][n] = conv4<3>(acc[ai][0][3][n], acc[ai][0][2][n], bp, fr, w0, w1, w2, bsv, db0 - 48);
;                 acc[ai][0][2][n] = conv4<2>(acc[ai][0][2][n], acc[ai][0][1][n], bp, fr, w0, w1, w2, bsv, db0 - 32);
;                 acc[ai][0][1][n] = conv4<1>(acc[ai][0][1][n], acc[ai][0][0][n], bp, fr, w0, w1, w2, bsv, db0 - 16);
;                 acc[ai][0][0][n] = conv4<0>(acc[ai][0][0][n], acc[ai][0][0][n], bp, fr, w0, w1, w2, bsv, db0);
.LBB0_1169:
	v_pk_fma_f32 v[76:77], v[170:171], v[158:159], v[162:163]
	v_pk_fma_f32 v[78:79], v[168:169], v[156:157], v[160:161]
	v_pk_fma_f32 v[54:55], v[150:151], v[54:55], v[76:77]
	v_pk_fma_f32 v[38:39], v[148:149], v[38:39], v[78:79]
	v_pk_fma_f32 v[106:107], v[26:27], v[52:53], v[54:55]
	v_pk_fma_f32 v[104:105], v[24:25], v[36:37], v[38:39]
	s_add_i32 s0, s2, -15
	v_mov_b32_dpp v38, v144 row_ror:1 row_mask:0xf bank_mask:0xf
	v_mov_b32_dpp v36, v144 row_ror:2 row_mask:0xf bank_mask:0xf
	v_mov_b32_dpp v39, v145 row_ror:1 row_mask:0xf bank_mask:0xf
	v_mov_b32_dpp v37, v145 row_ror:2 row_mask:0xf bank_mask:0xf
	v_mov_b32_dpp v54, v146 row_ror:1 row_mask:0xf bank_mask:0xf
	v_mov_b32_dpp v52, v146 row_ror:2 row_mask:0xf bank_mask:0xf
	v_mov_b32_dpp v55, v147 row_ror:1 row_mask:0xf bank_mask:0xf
	v_mov_b32_dpp v53, v147 row_ror:2 row_mask:0xf bank_mask:0xf
	s_cmp_gt_u32 s0, 16
	v_mov_b32_dpp v38, v164 row_shr:1 row_mask:0xf bank_mask:0xf
	v_mov_b32_dpp v36, v164 row_shr:2 row_mask:0xf bank_mask:0xf
	v_mov_b32_dpp v39, v165 row_shr:1 row_mask:0xf bank_mask:0xf
	v_mov_b32_dpp v37, v165 row_shr:2 row_mask:0xf bank_mask:0xf
	v_mov_b32_dpp v54, v166 row_shr:1 row_mask:0xf bank_mask:0xf
	v_mov_b32_dpp v52, v166 row_shr:2 row_mask:0xf bank_mask:0xf
	v_mov_b32_dpp v55, v167 row_shr:1 row_mask:0xf bank_mask:0xf
	v_mov_b32_dpp v53, v167 row_shr:2 row_mask:0xf bank_mask:0xf
	s_cselect_b64 s[10:11], -1, 0
	s_cmp_lt_u32 s0, 17
	s_mov_b64 s[0:1], -1
	s_cbranch_scc1 .LBB0_1171
	s_mov_b64 s[0:1], 0

; #define LAS __attribute__((address_space(3)))
;     template <int M_> __device__ __forceinline__ f32x4 conv4(const f32x4 c4, const f32x4 pg, const LAS float* bp, int fr, const f32x4 w0, const f32x4 w1, const f32x4 w2, const f32x4 bsv, int db) const {
;         f32x4 p1, p2;
;         if (M_ > 0) {
; #pragma unroll
;             for (int e = 0; e < 4; ++e) { p1[e] = dpp_f<0x111>(dpp_r<0x121>(pg[e]), c4[e]); p2[e] = dpp_f<0x112>(dpp_r<0x122>(pg[e]), c4[e]); }
;         } else {
;             const f32x4 x1 = *(const LAS f32x4*)(bp + 256), x2 = *(const LAS f32x4*)(bp + (fr & 1) * 256);
; #pragma unroll
;             for (int e = 0; e < 4; ++e) { p1[e] = dpp_f<0x111>(x1[e], c4[e]); p2[e] = dpp_f<0x112>(x2[e], c4[e]); }
;         }
;         if ((unsigned)(db + 1) < 17u) { const int d = fr - db;
; #pragma unroll
;             for (int e = 0; e < 4; ++e) { p1[e] = d == 0 ? 0.f : p1[e]; p2[e] = (unsigned)d < 2u ? 0.f : p2[e]; } }
;         f32x4 uu = bsv + w2 * c4 + w1 * p1 + w0 * p2;
;         asm volatile("" : "+v"(uu));
;         return uu;
;     }
;     __device__ __forceinline__ void prompt(f32x4 (&acc)[2][2][4][2], const Unit& u, int row0t, int wr, int wc, int fr, int fq) const {
;     ...
;                 const int db0 = rho_b - (ai * HALF + wr * 64);
;                 acc[ai][0][3][n] = conv4<3>(acc[ai][0][3][n], acc[ai][0][2][n], bp, fr, w0, w1, w2, bsv, db0 - 48);
;                 acc[ai][0][2][n] = conv4<2>(acc[ai][0][2][n], acc[ai][0][1][n], bp, fr, w0, w1, w2, bsv, db0 - 32);
;                 acc[ai][0][1][n] = conv4<1>(acc[ai][0][1][n], acc[ai][0][0][n], bp, fr, w0, w1, w2, bsv, db0 - 16);
;                 acc[ai][0][0][n] = conv4<0>(acc[ai][0][0][n], acc[ai][0][0][n], bp, fr, w0, w1, w2, bsv, db0);
.LBB0_1177:
	v_pk_fma_f32 v[76:77], v[146:147], v[158:159], v[162:163]
	v_pk_fma_f32 v[78:79], v[144:145], v[156:157], v[160:161]
	v_pk_fma_f32 v[54:55], v[150:151], v[54:55], v[76:77]
	v_pk_fma_f32 v[52:53], v[148:149], v[52:53], v[78:79]
	v_pk_fma_f32 v[78:79], v[26:27], v[38:39], v[54:55]
	v_pk_fma_f32 v[76:77], v[24:25], v[36:37], v[52:53]
	s_add_i32 s0, s2, 0xffffff51
	v_mov_b32_dpp v38, v44 row_ror:1 row_mask:0xf bank_mask:0xf
	v_mov_b32_dpp v36, v44 row_ror:2 row_mask:0xf bank_mask:0xf
	v_mov_b32_dpp v39, v45 row_ror:1 row_mask:0xf bank_mask:0xf
	v_mov_b32_dpp v37, v45 row_ror:2 row_mask:0xf bank_mask:0xf
	v_mov_b32_dpp v54, v46 row_ror:1 row_mask:0xf bank_mask:0xf
	v_mov_b32_dpp v52, v46 row_ror:2 row_mask:0xf bank_mask:0xf
	v_mov_b32_dpp v55, v47 row_ror:1 row_mask:0xf bank_mask:0xf
	v_mov_b32_dpp v53, v47 row_ror:2 row_mask:0xf bank_mask:0xf
	s_cmp_gt_u32 s0, 16
	v_mov_b32_dpp v38, v136 row_shr:1 row_mask:0xf bank_mask:0xf
	v_mov_b32_dpp v36, v136 row_shr:2 row_mask:0xf bank_mask:0xf
	v_mov_b32_dpp v39, v137 row_shr:1 row_mask:0xf bank_mask:0xf
	v_mov_b32_dpp v37, v137 row_shr:2 row_mask:0xf bank_mask:0xf
	v_mov_b32_dpp v54, v138 row_shr:1 row_mask:0xf bank_mask:0xf
	v_mov_b32_dpp v52, v138 row_shr:2 row_mask:0xf bank_mask:0xf
	v_mov_b32_dpp v55, v139 row_shr:1 row_mask:0xf bank_mask:0xf
	v_mov_b32_dpp v53, v139 row_shr:2 row_mask:0xf bank_mask:0xf
	s_cselect_b64 s[58:59], -1, 0
	s_cmp_lt_u32 s0, 17
	s_mov_b64 s[0:1], -1
	s_cbranch_scc1 .LBB0_1179
	s_mov_b64 s[0:1], 0

; #define LAS __attribute__((address_space(3)))
;     template <int M_> __device__ __forceinline__ f32x4 conv4(const f32x4 c4, const f32x4 pg, const LAS float* bp, int fr, const f32x4 w0, const f32x4 w1, const f32x4 w2, const f32x4 bsv, int db) const {
;         f32x4 p1, p2;
;         if (M_ > 0) {
; #pragma unroll
;             for (int e = 0; e < 4; ++e) { p1[e] = dpp_f<0x111>(dpp_r<0x121>(pg[e]), c4[e]); p2[e] = dpp_f<0x112>(dpp_r<0x122>(pg[e]), c4[e]); }
;         } else {
;             const f32x4 x1 = *(const LAS f32x4*)(bp + 256), x2 = *(const LAS f32x4*)(bp + (fr & 1) * 256);
; #pragma unroll
;             for (int e = 0; e < 4; ++e) { p1[e] = dpp_f<0x111>(x1[e], c4[e]); p2[e] = dpp_f<0x112>(x2[e], c4[e]); }
;         }
;         if ((unsigned)(db + 1) < 17u) { const int d = fr - db;
; #pragma unroll
;             for (int e = 0; e < 4; ++e) { p1[e] = d == 0 ? 0.f : p1[e]; p2[e] = (unsigned)d < 2u ? 0.f : p2[e]; } }
;         f32x4 uu = bsv + w2 * c4 + w1 * p1 + w0 * p2;
;         asm volatile("" : "+v"(uu));
;         return uu;
;     }
;     __device__ __forceinline__ void prompt(f32x4 (&acc)[2][2][4][2], const Unit& u, int row0t, int wr, int wc, int fr, int fq) const {
;     ...
;                 const int db0 = rho_b - (ai * HALF + wr * 64);
;                 acc[ai][0][3][n] = conv4<3>(acc[ai][0][3][n], acc[ai][0][2][n], bp, fr, w0, w1, w2, bsv, db0 - 48);
;                 acc[ai][0][2][n] = conv4<2>(acc[ai][0][2][n], acc[ai][0][1][n], bp, fr, w0, w1, w2, bsv, db0 - 32);
;                 acc[ai][0][1][n] = conv4<1>(acc[ai][0][1][n], acc[ai][0][0][n], bp, fr, w0, w1, w2, bsv, db0 - 16);
;                 acc[ai][0][0][n] = conv4<0>(acc[ai][0][0][n], acc[ai][0][0][n], bp, fr, w0, w1, w2, bsv, db0);
.LBB0_1181:
	v_pk_fma_f32 v[138:139], v[138:139], v[158:159], v[162:163]
	v_pk_fma_f32 v[136:137], v[136:137], v[156:157], v[160:161]
	v_pk_fma_f32 v[54:55], v[150:151], v[54:55], v[138:139]
	v_pk_fma_f32 v[38:39], v[148:149], v[38:39], v[136:137]
	v_pk_fma_f32 v[54:55], v[26:27], v[52:53], v[54:55]
	v_pk_fma_f32 v[52:53], v[24:25], v[36:37], v[38:39]
	s_add_i32 s0, s2, 0xffffff61
	v_mov_b32_dpp v38, v140 row_ror:1 row_mask:0xf bank_mask:0xf
	v_mov_b32_dpp v36, v140 row_ror:2 row_mask:0xf bank_mask:0xf
	v_mov_b32_dpp v39, v141 row_ror:1 row_mask:0xf bank_mask:0xf
	v_mov_b32_dpp v37, v141 row_ror:2 row_mask:0xf bank_mask:0xf
	v_mov_b32_dpp v138, v142 row_ror:1 row_mask:0xf bank_mask:0xf
	v_mov_b32_dpp v136, v142 row_ror:2 row_mask:0xf bank_mask:0xf
	v_mov_b32_dpp v139, v143 row_ror:1 row_mask:0xf bank_mask:0xf
	v_mov_b32_dpp v137, v143 row_ror:2 row_mask:0xf bank_mask:0xf
	s_cmp_gt_u32 s0, 16
	v_mov_b32_dpp v38, v44 row_shr:1 row_mask:0xf bank_mask:0xf
	v_mov_b32_dpp v36, v44 row_shr:2 row_mask:0xf bank_mask:0xf
	v_mov_b32_dpp v39, v45 row_shr:1 row_mask:0xf bank_mask:0xf
	v_mov_b32_dpp v37, v45 row_shr:2 row_mask:0xf bank_mask:0xf
	v_mov_b32_dpp v138, v46 row_shr:1 row_mask:0xf bank_mask:0xf
	v_mov_b32_dpp v136, v46 row_shr:2 row_mask:0xf bank_mask:0xf
	v_mov_b32_dpp v139, v47 row_shr:1 row_mask:0xf bank_mask:0xf
	v_mov_b32_dpp v137, v47 row_shr:2 row_mask:0xf bank_mask:0xf
	s_cselect_b64 s[64:65], -1, 0
	s_cmp_lt_u32 s0, 17
	s_mov_b64 s[0:1], -1
	s_cbranch_scc1 .LBB0_1183
	s_mov_b64 s[0:1], 0

; #define LAS __attribute__((address_space(3)))
;     template <int M_> __device__ __forceinline__ f32x4 conv4(const f32x4 c4, const f32x4 pg, const LAS float* bp, int fr, const f32x4 w0, const f32x4 w1, const f32x4 w2, const f32x4 bsv, int db) const {
;         f32x4 p1, p2;
;         if (M_ > 0) {
; #pragma unroll
;             for (int e = 0; e < 4; ++e) { p1[e] = dpp_f<0x111>(dpp_r<0x121>(pg[e]), c4[e]); p2[e] = dpp_f<0x112>(dpp_r<0x122>(pg[e]), c4[e]); }
;         } else {
;             const f32x4 x1 = *(const LAS f32x4*)(bp + 256), x2 = *(const LAS f32x4*)(bp + (fr & 1) * 256);
; #pragma unroll
;             for (int e = 0; e < 4; ++e) { p1[e] = dpp_f<0x111>(x1[e], c4[e]); p2[e] = dpp_f<0x112>(x2[e], c4[e]); }
;         }
;         if ((unsigned)(db + 1) < 17u) { const int d = fr - db;
; #pragma unroll
;             for (int e = 0; e < 4; ++e) { p1[e] = d == 0 ? 0.f : p1[e]; p2[e] = (unsigned)d < 2u ? 0.f : p2[e]; } }
;         f32x4 uu = bsv + w2 * c4 + w1 * p1 + w0 * p2;
;         asm volatile("" : "+v"(uu));
;         return uu;
;     }
;     __device__ __forceinline__ void prompt(f32x4 (&acc)[2][2][4][2], const Unit& u, int row0t, int wr, int wc, int fr, int fq) const {
;     ...
;                 const int db0 = rho_b - (ai * HALF + wr * 64);
;                 acc[ai][0][3][n] = conv4<3>(acc[ai][0][3][n], acc[ai][0][2][n], bp, fr, w0, w1, w2, bsv, db0 - 48);
;                 acc[ai][0][2][n] = conv4<2>(acc[ai][0][2][n], acc[ai][0][1][n], bp, fr, w0, w1, w2, bsv, db0 - 32);
;                 acc[ai][0][1][n] = conv4<1>(acc[ai][0][1][n], acc[ai][0][0][n], bp, fr, w0, w1, w2, bsv, db0 - 16);
;                 acc[ai][0][0][n] = conv4<0>(acc[ai][0][0][n], acc[ai][0][0][n], bp, fr, w0, w1, w2, bsv, db0);
.LBB0_1185:
	v_pk_fma_f32 v[46:47], v[46:47], v[158:159], v[162:163]
	v_pk_fma_f32 v[44:45], v[44:45], v[156:157], v[160:161]
	v_pk_fma_f32 v[46:47], v[150:151], v[138:139], v[46:47]
	v_pk_fma_f32 v[38:39], v[148:149], v[38:39], v[44:45]
	v_pk_fma_f32 v[46:47], v[26:27], v[136:137], v[46:47]
	v_pk_fma_f32 v[44:45], v[24:25], v[36:37], v[38:39]
	s_add_i32 s0, s2, 0xffffff71
	v_mov_b32_dpp v38, v132 row_ror:1 row_mask:0xf bank_mask:0xf
	v_mov_b32_dpp v36, v132 row_ror:2 row_mask:0xf bank_mask:0xf
	v_mov_b32_dpp v39, v133 row_ror:1 row_mask:0xf bank_mask:0xf
	v_mov_b32_dpp v37, v133 row_ror:2 row_mask:0xf bank_mask:0xf
	v_mov_b32_dpp v138, v134 row_ror:1 row_mask:0xf bank_mask:0xf
	v_mov_b32_dpp v136, v134 row_ror:2 row_mask:0xf bank_mask:0xf
	v_mov_b32_dpp v139, v135 row_ror:1 row_mask:0xf bank_mask:0xf
	v_mov_b32_dpp v137, v135 row_ror:2 row_mask:0xf bank_mask:0xf
	s_cmp_gt_u32 s0, 16
	v_mov_b32_dpp v38, v140 row_shr:1 row_mask:0xf bank_mask:0xf
	v_mov_b32_dpp v36, v140 row_shr:2 row_mask:0xf bank_mask:0xf
	v_mov_b32_dpp v39, v141 row_shr:1 row_mask:0xf bank_mask:0xf
	v_mov_b32_dpp v37, v141 row_shr:2 row_mask:0xf bank_mask:0xf
	v_mov_b32_dpp v138, v142 row_shr:1 row_mask:0xf bank_mask:0xf
	v_mov_b32_dpp v136, v142 row_shr:2 row_mask:0xf bank_mask:0xf
	v_mov_b32_dpp v139, v143 row_shr:1 row_mask:0xf bank_mask:0xf
	v_mov_b32_dpp v137, v143 row_shr:2 row_mask:0xf bank_mask:0xf
	s_cselect_b64 s[68:69], -1, 0
	s_cmp_lt_u32 s0, 17
	s_mov_b64 s[0:1], -1
	s_cbranch_scc1 .LBB0_1187
	s_mov_b64 s[0:1], 0

; #define LAS __attribute__((address_space(3)))
;     template <int M_> __device__ __forceinline__ f32x4 conv4(const f32x4 c4, const f32x4 pg, const LAS float* bp, int fr, const f32x4 w0, const f32x4 w1, const f32x4 w2, const f32x4 bsv, int db) const {
;         f32x4 p1, p2;
;         if (M_ > 0) {
; #pragma unroll
;             for (int e = 0; e < 4; ++e) { p1[e] = dpp_f<0x111>(dpp_r<0x121>(pg[e]), c4[e]); p2[e] = dpp_f<0x112>(dpp_r<0x122>(pg[e]), c4[e]); }
;         } else {
;             const f32x4 x1 = *(const LAS f32x4*)(bp + 256), x2 = *(const LAS f32x4*)(bp + (fr & 1) * 256);
; #pragma unroll
;             for (int e = 0; e < 4; ++e) { p1[e] = dpp_f<0x111>(x1[e], c4[e]); p2[e] = dpp_f<0x112>(x2[e], c4[e]); }
;         }
;         if ((unsigned)(db + 1) < 17u) { const int d = fr - db;
; #pragma unroll
;             for (int e = 0; e < 4; ++e) { p1[e] = d == 0 ? 0.f : p1[e]; p2[e] = (unsigned)d < 2u ? 0.f : p2[e]; } }
;         f32x4 uu = bsv + w2 * c4 + w1 * p1 + w0 * p2;
;         asm volatile("" : "+v"(uu));
;         return uu;
;     }
;     __device__ __forceinline__ void prompt(f32x4 (&acc)[2][2][4][2], const Unit& u, int row0t, int wr, int wc, int fr, int fq) const {
;     ...
;         for (int n = 0; n < 2; ++n) {
;             const unsigned cso = (unsigned)((ca + 4 * n) * 4);
;             const f32x4 w0 = *(const f32x4*)((const char*)cw + cso), w1 = *(const f32x4*)((const char*)(cw + DFF2) + cso), w2 = *(const f32x4*)((const char*)(cw + 2 * DFF2) + cso), bsv = *(const f32x4*)((const char*)cb + cso);
; #pragma unroll
;             for (int ai = 0; ai < 2; ++ai) {
;                 int ps = ai * 2 + wr - 1; ps = ps < 0 ? 0 : ps;
;                 const LAS float* bp = bnd + (ps * 2) * 256 + cl + 4 * n;
;                 const int db0 = rho_b - (ai * HALF + wr * 64);
;                 acc[ai][0][3][n] = conv4<3>(acc[ai][0][3][n], acc[ai][0][2][n], bp, fr, w0, w1, w2, bsv, db0 - 48);
;                 acc[ai][0][2][n] = conv4<2>(acc[ai][0][2][n], acc[ai][0][1][n], bp, fr, w0, w1, w2, bsv, db0 - 32);
;                 acc[ai][0][1][n] = conv4<1>(acc[ai][0][1][n], acc[ai][0][0][n], bp, fr, w0, w1, w2, bsv, db0 - 16);
;                 acc[ai][0][0][n] = conv4<0>(acc[ai][0][0][n], acc[ai][0][0][n], bp, fr, w0, w1, w2, bsv, db0);
;             }
.LBB0_1193:
	v_pk_fma_f32 v[134:135], v[134:135], v[158:159], v[162:163]
	v_pk_fma_f32 v[132:133], v[132:133], v[156:157], v[160:161]
	v_pk_fma_f32 v[134:135], v[150:151], v[142:143], v[134:135]
	v_pk_fma_f32 v[132:133], v[148:149], v[140:141], v[132:133]
	v_pk_fma_f32 v[26:27], v[26:27], v[138:139], v[134:135]
	v_pk_fma_f32 v[24:25], v[24:25], v[136:137], v[132:133]
	v_add_u32_e32 v18, 16, v175
	global_load_dwordx4 v[140:143], v18, s[54:55]
	global_load_dwordx4 v[144:147], v18, s[34:35]
	global_load_dwordx4 v[136:139], v18, s[96:97]
	global_load_dwordx4 v[148:151], v18, s[66:67]
	v_mov_b32_dpp v134, v128 row_ror:1 row_mask:0xf bank_mask:0xf
	v_mov_b32_dpp v132, v128 row_ror:2 row_mask:0xf bank_mask:0xf
	v_mov_b32_dpp v135, v129 row_ror:1 row_mask:0xf bank_mask:0xf
	v_mov_b32_dpp v133, v129 row_ror:2 row_mask:0xf bank_mask:0xf
	v_mov_b32_dpp v154, v130 row_ror:1 row_mask:0xf bank_mask:0xf
	v_mov_b32_dpp v152, v130 row_ror:2 row_mask:0xf bank_mask:0xf
	v_mov_b32_dpp v155, v131 row_ror:1 row_mask:0xf bank_mask:0xf
	v_mov_b32_dpp v153, v131 row_ror:2 row_mask:0xf bank_mask:0xf
	v_cndmask_b32_e64 v18, 0, 1, s[6:7]
	v_mov_b32_dpp v134, v116 row_shr:1 row_mask:0xf bank_mask:0xf
	v_mov_b32_dpp v132, v116 row_shr:2 row_mask:0xf bank_mask:0xf
	v_mov_b32_dpp v135, v117 row_shr:1 row_mask:0xf bank_mask:0xf
	v_mov_b32_dpp v133, v117 row_shr:2 row_mask:0xf bank_mask:0xf
	v_mov_b32_dpp v154, v118 row_shr:1 row_mask:0xf bank_mask:0xf
	v_mov_b32_dpp v152, v118 row_shr:2 row_mask:0xf bank_mask:0xf
	v_mov_b32_dpp v155, v119 row_shr:1 row_mask:0xf bank_mask:0xf
	v_mov_b32_dpp v153, v119 row_shr:2 row_mask:0xf bank_mask:0xf
	v_cmp_ne_u32_e64 s[20:21], 1, v18
	s_andn2_b64 vcc, exec, s[6:7]
	s_mov_b64 s[0:1], -1
	s_cbranch_vccnz .LBB0_1195
	s_mov_b64 s[0:1], 0

; #define LAS __attribute__((address_space(3)))
;     template <int M_> __device__ __forceinline__ f32x4 conv4(const f32x4 c4, const f32x4 pg, const LAS float* bp, int fr, const f32x4 w0, const f32x4 w1, const f32x4 w2, const f32x4 bsv, int db) const {
;         f32x4 p1, p2;
;         if (M_ > 0) {
; #pragma unroll
;             for (int e = 0; e < 4; ++e) { p1[e] = dpp_f<0x111>(dpp_r<0x121>(pg[e]), c4[e]); p2[e] = dpp_f<0x112>(dpp_r<0x122>(pg[e]), c4[e]); }
;         } else {
;             const f32x4 x1 = *(const LAS f32x4*)(bp + 256), x2 = *(const LAS f32x4*)(bp + (fr & 1) * 256);
; #pragma unroll
;             for (int e = 0; e < 4; ++e) { p1[e] = dpp_f<0x111>(x1[e], c4[e]); p2[e] = dpp_f<0x112>(x2[e], c4[e]); }
;         }
;         if ((unsigned)(db + 1) < 17u) { const int d = fr - db;
; #pragma unroll
;             for (int e = 0; e < 4; ++e) { p1[e] = d == 0 ? 0.f : p1[e]; p2[e] = (unsigned)d < 2u ? 0.f : p2[e]; } }
;         f32x4 uu = bsv + w2 * c4 + w1 * p1 + w0 * p2;
;         asm volatile("" : "+v"(uu));
;         return uu;
;     }
;     __device__ __forceinline__ void prompt(f32x4 (&acc)[2][2][4][2], const Unit& u, int row0t, int wr, int wc, int fr, int fq) const {
;     ...
;                 const int db0 = rho_b - (ai * HALF + wr * 64);
;                 acc[ai][0][3][n] = conv4<3>(acc[ai][0][3][n], acc[ai][0][2][n], bp, fr, w0, w1, w2, bsv, db0 - 48);
;                 acc[ai][0][2][n] = conv4<2>(acc[ai][0][2][n], acc[ai][0][1][n], bp, fr, w0, w1, w2, bsv, db0 - 32);
;                 acc[ai][0][1][n] = conv4<1>(acc[ai][0][1][n], acc[ai][0][0][n], bp, fr, w0, w1, w2, bsv, db0 - 16);
;                 acc[ai][0][0][n] = conv4<0>(acc[ai][0][0][n], acc[ai][0][0][n], bp, fr, w0, w1, w2, bsv, db0);
.LBB0_1197:
	s_waitcnt vmcnt(0)
	v_pk_fma_f32 v[118:119], v[118:119], v[146:147], v[150:151]
	v_pk_fma_f32 v[116:117], v[116:117], v[144:145], v[148:149]
	v_pk_fma_f32 v[118:119], v[142:143], v[154:155], v[118:119]
	v_pk_fma_f32 v[116:117], v[140:141], v[134:135], v[116:117]
	v_pk_fma_f32 v[134:135], v[138:139], v[152:153], v[118:119]
	v_pk_fma_f32 v[132:133], v[136:137], v[132:133], v[116:117]
	v_mov_b32_dpp v118, v124 row_ror:1 row_mask:0xf bank_mask:0xf
	v_mov_b32_dpp v116, v124 row_ror:2 row_mask:0xf bank_mask:0xf
	v_mov_b32_dpp v119, v125 row_ror:1 row_mask:0xf bank_mask:0xf
	v_mov_b32_dpp v117, v125 row_ror:2 row_mask:0xf bank_mask:0xf
	v_mov_b32_dpp v154, v126 row_ror:1 row_mask:0xf bank_mask:0xf
	v_mov_b32_dpp v152, v126 row_ror:2 row_mask:0xf bank_mask:0xf
	v_mov_b32_dpp v155, v127 row_ror:1 row_mask:0xf bank_mask:0xf
	v_mov_b32_dpp v153, v127 row_ror:2 row_mask:0xf bank_mask:0xf
	v_cndmask_b32_e64 v18, 0, 1, s[8:9]
	v_mov_b32_dpp v118, v128 row_shr:1 row_mask:0xf bank_mask:0xf
	v_mov_b32_dpp v116, v128 row_shr:2 row_mask:0xf bank_mask:0xf
	v_mov_b32_dpp v119, v129 row_shr:1 row_mask:0xf bank_mask:0xf
	v_mov_b32_dpp v117, v129 row_shr:2 row_mask:0xf bank_mask:0xf
	v_mov_b32_dpp v154, v130 row_shr:1 row_mask:0xf bank_mask:0xf
	v_mov_b32_dpp v152, v130 row_shr:2 row_mask:0xf bank_mask:0xf
	v_mov_b32_dpp v155, v131 row_shr:1 row_mask:0xf bank_mask:0xf
	v_mov_b32_dpp v153, v131 row_shr:2 row_mask:0xf bank_mask:0xf
	v_cmp_ne_u32_e64 s[18:19], 1, v18
	s_andn2_b64 vcc, exec, s[8:9]
	s_mov_b64 s[0:1], -1
	s_cbranch_vccnz .LBB0_1199
	s_mov_b64 s[0:1], 0

; #define LAS __attribute__((address_space(3)))
;     template <int M_> __device__ __forceinline__ f32x4 conv4(const f32x4 c4, const f32x4 pg, const LAS float* bp, int fr, const f32x4 w0, const f32x4 w1, const f32x4 w2, const f32x4 bsv, int db) const {
;         f32x4 p1, p2;
;         if (M_ > 0) {
; #pragma unroll
;             for (int e = 0; e < 4; ++e) { p1[e] = dpp_f<0x111>(dpp_r<0x121>(pg[e]), c4[e]); p2[e] = dpp_f<0x112>(dpp_r<0x122>(pg[e]), c4[e]); }
;         } else {
;             const f32x4 x1 = *(const LAS f32x4*)(bp + 256), x2 = *(const LAS f32x4*)(bp + (fr & 1) * 256);
; #pragma unroll
;             for (int e = 0; e < 4; ++e) { p1[e] = dpp_f<0x111>(x1[e], c4[e]); p2[e] = dpp_f<0x112>(x2[e], c4[e]); }
;         }
;         if ((unsigned)(db + 1) < 17u) { const int d = fr - db;
; #pragma unroll
;             for (int e = 0; e < 4; ++e) { p1[e] = d == 0 ? 0.f : p1[e]; p2[e] = (unsigned)d < 2u ? 0.f : p2[e]; } }
;         f32x4 uu = bsv + w2 * c4 + w1 * p1 + w0 * p2;
;         asm volatile("" : "+v"(uu));
;         return uu;
;     }
;     __device__ __forceinline__ void prompt(f32x4 (&acc)[2][2][4][2], const Unit& u, int row0t, int wr, int wc, int fr, int fq) const {
;     ...
;                 const int db0 = rho_b - (ai * HALF + wr * 64);
;                 acc[ai][0][3][n] = conv4<3>(acc[ai][0][3][n], acc[ai][0][2][n], bp, fr, w0, w1, w2, bsv, db0 - 48);
;                 acc[ai][0][2][n] = conv4<2>(acc[ai][0][2][n], acc[ai][0][1][n], bp, fr, w0, w1, w2, bsv, db0 - 32);
;                 acc[ai][0][1][n] = conv4<1>(acc[ai][0][1][n], acc[ai][0][0][n], bp, fr, w0, w1, w2, bsv, db0 - 16);
;                 acc[ai][0][0][n] = conv4<0>(acc[ai][0][0][n], acc[ai][0][0][n], bp, fr, w0, w1, w2, bsv, db0);
.LBB0_1201:
	v_pk_fma_f32 v[130:131], v[130:131], v[146:147], v[150:151]
	v_pk_fma_f32 v[128:129], v[128:129], v[144:145], v[148:149]
	v_pk_fma_f32 v[130:131], v[142:143], v[154:155], v[130:131]
	v_pk_fma_f32 v[118:119], v[140:141], v[118:119], v[128:129]
	v_pk_fma_f32 v[130:131], v[138:139], v[152:153], v[130:131]
	v_pk_fma_f32 v[128:129], v[136:137], v[116:117], v[118:119]
	v_mov_b32_dpp v118, v100 row_ror:1 row_mask:0xf bank_mask:0xf
	v_mov_b32_dpp v116, v100 row_ror:2 row_mask:0xf bank_mask:0xf
	v_mov_b32_dpp v119, v101 row_ror:1 row_mask:0xf bank_mask:0xf
	v_mov_b32_dpp v117, v101 row_ror:2 row_mask:0xf bank_mask:0xf
	v_mov_b32_dpp v154, v102 row_ror:1 row_mask:0xf bank_mask:0xf
	v_mov_b32_dpp v152, v102 row_ror:2 row_mask:0xf bank_mask:0xf
	v_mov_b32_dpp v155, v103 row_ror:1 row_mask:0xf bank_mask:0xf
	v_mov_b32_dpp v153, v103 row_ror:2 row_mask:0xf bank_mask:0xf
	v_cndmask_b32_e64 v18, 0, 1, s[10:11]
	v_mov_b32_dpp v118, v124 row_shr:1 row_mask:0xf bank_mask:0xf
	v_mov_b32_dpp v116, v124 row_shr:2 row_mask:0xf bank_mask:0xf
	v_mov_b32_dpp v119, v125 row_shr:1 row_mask:0xf bank_mask:0xf
	v_mov_b32_dpp v117, v125 row_shr:2 row_mask:0xf bank_mask:0xf
	v_mov_b32_dpp v154, v126 row_shr:1 row_mask:0xf bank_mask:0xf
	v_mov_b32_dpp v152, v126 row_shr:2 row_mask:0xf bank_mask:0xf
	v_mov_b32_dpp v155, v127 row_shr:1 row_mask:0xf bank_mask:0xf
	v_mov_b32_dpp v153, v127 row_shr:2 row_mask:0xf bank_mask:0xf
	v_cmp_ne_u32_e64 s[16:17], 1, v18
	s_andn2_b64 vcc, exec, s[10:11]
	s_mov_b64 s[0:1], -1
	s_cbranch_vccnz .LBB0_1203
	s_mov_b64 s[0:1], 0

; #define LAS __attribute__((address_space(3)))
;     template <int M_> __device__ __forceinline__ f32x4 conv4(const f32x4 c4, const f32x4 pg, const LAS float* bp, int fr, const f32x4 w0, const f32x4 w1, const f32x4 w2, const f32x4 bsv, int db) const {
;         f32x4 p1, p2;
;         if (M_ > 0) {
; #pragma unroll
;             for (int e = 0; e < 4; ++e) { p1[e] = dpp_f<0x111>(dpp_r<0x121>(pg[e]), c4[e]); p2[e] = dpp_f<0x112>(dpp_r<0x122>(pg[e]), c4[e]); }
;         } else {
;             const f32x4 x1 = *(const LAS f32x4*)(bp + 256), x2 = *(const LAS f32x4*)(bp + (fr & 1) * 256);
; #pragma unroll
;             for (int e = 0; e < 4; ++e) { p1[e] = dpp_f<0x111>(x1[e], c4[e]); p2[e] = dpp_f<0x112>(x2[e], c4[e]); }
;         }
;         if ((unsigned)(db + 1) < 17u) { const int d = fr - db;
; #pragma unroll
;             for (int e = 0; e < 4; ++e) { p1[e] = d == 0 ? 0.f : p1[e]; p2[e] = (unsigned)d < 2u ? 0.f : p2[e]; } }
;         f32x4 uu = bsv + w2 * c4 + w1 * p1 + w0 * p2;
;         asm volatile("" : "+v"(uu));
;         return uu;
;     }
;     __device__ __forceinline__ void prompt(f32x4 (&acc)[2][2][4][2], const Unit& u, int row0t, int wr, int wc, int fr, int fq) const {
;     ...
;                 const int db0 = rho_b - (ai * HALF + wr * 64);
;                 acc[ai][0][3][n] = conv4<3>(acc[ai][0][3][n], acc[ai][0][2][n], bp, fr, w0, w1, w2, bsv, db0 - 48);
;                 acc[ai][0][2][n] = conv4<2>(acc[ai][0][2][n], acc[ai][0][1][n], bp, fr, w0, w1, w2, bsv, db0 - 32);
;                 acc[ai][0][1][n] = conv4<1>(acc[ai][0][1][n], acc[ai][0][0][n], bp, fr, w0, w1, w2, bsv, db0 - 16);
;                 acc[ai][0][0][n] = conv4<0>(acc[ai][0][0][n], acc[ai][0][0][n], bp, fr, w0, w1, w2, bsv, db0);
.LBB0_1209:
	v_pk_fma_f32 v[102:103], v[102:103], v[146:147], v[150:151]
	v_pk_fma_f32 v[100:101], v[100:101], v[144:145], v[148:149]
	v_pk_fma_f32 v[102:103], v[142:143], v[154:155], v[102:103]
	v_pk_fma_f32 v[100:101], v[140:141], v[152:153], v[100:101]
	v_pk_fma_f32 v[118:119], v[138:139], v[118:119], v[102:103]
	v_pk_fma_f32 v[116:117], v[136:137], v[116:117], v[100:101]
	v_mov_b32_dpp v102, v80 row_ror:1 row_mask:0xf bank_mask:0xf
	v_mov_b32_dpp v100, v80 row_ror:2 row_mask:0xf bank_mask:0xf
	v_mov_b32_dpp v103, v81 row_ror:1 row_mask:0xf bank_mask:0xf
	v_mov_b32_dpp v101, v81 row_ror:2 row_mask:0xf bank_mask:0xf
	v_mov_b32_dpp v154, v82 row_ror:1 row_mask:0xf bank_mask:0xf
	v_mov_b32_dpp v152, v82 row_ror:2 row_mask:0xf bank_mask:0xf
	v_mov_b32_dpp v155, v83 row_ror:1 row_mask:0xf bank_mask:0xf
	v_mov_b32_dpp v153, v83 row_ror:2 row_mask:0xf bank_mask:0xf
	v_cndmask_b32_e64 v18, 0, 1, s[58:59]
	v_mov_b32_dpp v102, v72 row_shr:1 row_mask:0xf bank_mask:0xf
	v_mov_b32_dpp v100, v72 row_shr:2 row_mask:0xf bank_mask:0xf
	v_mov_b32_dpp v103, v73 row_shr:1 row_mask:0xf bank_mask:0xf
	v_mov_b32_dpp v101, v73 row_shr:2 row_mask:0xf bank_mask:0xf
	v_mov_b32_dpp v154, v74 row_shr:1 row_mask:0xf bank_mask:0xf
	v_mov_b32_dpp v152, v74 row_shr:2 row_mask:0xf bank_mask:0xf
	v_mov_b32_dpp v155, v75 row_shr:1 row_mask:0xf bank_mask:0xf
	v_mov_b32_dpp v153, v75 row_shr:2 row_mask:0xf bank_mask:0xf
	v_cmp_ne_u32_e64 s[12:13], 1, v18
	s_andn2_b64 vcc, exec, s[58:59]
	s_mov_b64 s[0:1], -1
	s_cbranch_vccnz .LBB0_1211
	s_mov_b64 s[0:1], 0

; #define LAS __attribute__((address_space(3)))
;     template <int M_> __device__ __forceinline__ f32x4 conv4(const f32x4 c4, const f32x4 pg, const LAS float* bp, int fr, const f32x4 w0, const f32x4 w1, const f32x4 w2, const f32x4 bsv, int db) const {
;         f32x4 p1, p2;
;         if (M_ > 0) {
; #pragma unroll
;             for (int e = 0; e < 4; ++e) { p1[e] = dpp_f<0x111>(dpp_r<0x121>(pg[e]), c4[e]); p2[e] = dpp_f<0x112>(dpp_r<0x122>(pg[e]), c4[e]); }
;         } else {
;             const f32x4 x1 = *(const LAS f32x4*)(bp + 256), x2 = *(const LAS f32x4*)(bp + (fr & 1) * 256);
; #pragma unroll
;             for (int e = 0; e < 4; ++e) { p1[e] = dpp_f<0x111>(x1[e], c4[e]); p2[e] = dpp_f<0x112>(x2[e], c4[e]); }
;         }
;         if ((unsigned)(db + 1) < 17u) { const int d = fr - db;
; #pragma unroll
;             for (int e = 0; e < 4; ++e) { p1[e] = d == 0 ? 0.f : p1[e]; p2[e] = (unsigned)d < 2u ? 0.f : p2[e]; } }
;         f32x4 uu = bsv + w2 * c4 + w1 * p1 + w0 * p2;
;         asm volatile("" : "+v"(uu));
;         return uu;
;     }
;     __device__ __forceinline__ void prompt(f32x4 (&acc)[2][2][4][2], const Unit& u, int row0t, int wr, int wc, int fr, int fq) const {
;     ...
;                 const int db0 = rho_b - (ai * HALF + wr * 64);
;                 acc[ai][0][3][n] = conv4<3>(acc[ai][0][3][n], acc[ai][0][2][n], bp, fr, w0, w1, w2, bsv, db0 - 48);
;                 acc[ai][0][2][n] = conv4<2>(acc[ai][0][2][n], acc[ai][0][1][n], bp, fr, w0, w1, w2, bsv, db0 - 32);
;                 acc[ai][0][1][n] = conv4<1>(acc[ai][0][1][n], acc[ai][0][0][n], bp, fr, w0, w1, w2, bsv, db0 - 16);
;                 acc[ai][0][0][n] = conv4<0>(acc[ai][0][0][n], acc[ai][0][0][n], bp, fr, w0, w1, w2, bsv, db0);
.LBB0_1213:
	v_pk_fma_f32 v[74:75], v[74:75], v[146:147], v[150:151]
	v_pk_fma_f32 v[72:73], v[72:73], v[144:145], v[148:149]
	v_pk_fma_f32 v[74:75], v[142:143], v[154:155], v[74:75]
	v_pk_fma_f32 v[72:73], v[140:141], v[102:103], v[72:73]
	v_pk_fma_f32 v[102:103], v[138:139], v[152:153], v[74:75]
	v_pk_fma_f32 v[100:101], v[136:137], v[100:101], v[72:73]
	v_mov_b32_dpp v74, v120 row_ror:1 row_mask:0xf bank_mask:0xf
	v_mov_b32_dpp v72, v120 row_ror:2 row_mask:0xf bank_mask:0xf
	v_mov_b32_dpp v75, v121 row_ror:1 row_mask:0xf bank_mask:0xf
	v_mov_b32_dpp v73, v121 row_ror:2 row_mask:0xf bank_mask:0xf
	v_mov_b32_dpp v154, v122 row_ror:1 row_mask:0xf bank_mask:0xf
	v_mov_b32_dpp v152, v122 row_ror:2 row_mask:0xf bank_mask:0xf
	v_mov_b32_dpp v155, v123 row_ror:1 row_mask:0xf bank_mask:0xf
	v_mov_b32_dpp v153, v123 row_ror:2 row_mask:0xf bank_mask:0xf
	v_cndmask_b32_e64 v18, 0, 1, s[64:65]
	v_mov_b32_dpp v74, v80 row_shr:1 row_mask:0xf bank_mask:0xf
	v_mov_b32_dpp v72, v80 row_shr:2 row_mask:0xf bank_mask:0xf
	v_mov_b32_dpp v75, v81 row_shr:1 row_mask:0xf bank_mask:0xf
	v_mov_b32_dpp v73, v81 row_shr:2 row_mask:0xf bank_mask:0xf
	v_mov_b32_dpp v154, v82 row_shr:1 row_mask:0xf bank_mask:0xf
	v_mov_b32_dpp v152, v82 row_shr:2 row_mask:0xf bank_mask:0xf
	v_mov_b32_dpp v155, v83 row_shr:1 row_mask:0xf bank_mask:0xf
	v_mov_b32_dpp v153, v83 row_shr:2 row_mask:0xf bank_mask:0xf
	v_cmp_ne_u32_e64 s[10:11], 1, v18
	s_andn2_b64 vcc, exec, s[64:65]
	s_mov_b64 s[0:1], -1
	s_cbranch_vccnz .LBB0_1215
	s_mov_b64 s[0:1], 0

; #define LAS __attribute__((address_space(3)))
;     template <int M_> __device__ __forceinline__ f32x4 conv4(const f32x4 c4, const f32x4 pg, const LAS float* bp, int fr, const f32x4 w0, const f32x4 w1, const f32x4 w2, const f32x4 bsv, int db) const {
;         f32x4 p1, p2;
;         if (M_ > 0) {
; #pragma unroll
;             for (int e = 0; e < 4; ++e) { p1[e] = dpp_f<0x111>(dpp_r<0x121>(pg[e]), c4[e]); p2[e] = dpp_f<0x112>(dpp_r<0x122>(pg[e]), c4[e]); }
;         } else {
;             const f32x4 x1 = *(const LAS f32x4*)(bp + 256), x2 = *(const LAS f32x4*)(bp + (fr & 1) * 256);
; #pragma unroll
;             for (int e = 0; e < 4; ++e) { p1[e] = dpp_f<0x111>(x1[e], c4[e]); p2[e] = dpp_f<0x112>(x2[e], c4[e]); }
;         }
;         if ((unsigned)(db + 1) < 17u) { const int d = fr - db;
; #pragma unroll
;             for (int e = 0; e < 4; ++e) { p1[e] = d == 0 ? 0.f : p1[e]; p2[e] = (unsigned)d < 2u ? 0.f : p2[e]; } }
;         f32x4 uu = bsv + w2 * c4 + w1 * p1 + w0 * p2;
;         asm volatile("" : "+v"(uu));
;         return uu;
;     }
;     __device__ __forceinline__ void prompt(f32x4 (&acc)[2][2][4][2], const Unit& u, int row0t, int wr, int wc, int fr, int fq) const {
;     ...
;                 const int db0 = rho_b - (ai * HALF + wr * 64);
;                 acc[ai][0][3][n] = conv4<3>(acc[ai][0][3][n], acc[ai][0][2][n], bp, fr, w0, w1, w2, bsv, db0 - 48);
;                 acc[ai][0][2][n] = conv4<2>(acc[ai][0][2][n], acc[ai][0][1][n], bp, fr, w0, w1, w2, bsv, db0 - 32);
;                 acc[ai][0][1][n] = conv4<1>(acc[ai][0][1][n], acc[ai][0][0][n], bp, fr, w0, w1, w2, bsv, db0 - 16);
;                 acc[ai][0][0][n] = conv4<0>(acc[ai][0][0][n], acc[ai][0][0][n], bp, fr, w0, w1, w2, bsv, db0);
.LBB0_1217:
	v_pk_fma_f32 v[82:83], v[82:83], v[146:147], v[150:151]
	v_pk_fma_f32 v[80:81], v[80:81], v[144:145], v[148:149]
	v_pk_fma_f32 v[82:83], v[142:143], v[154:155], v[82:83]
	v_pk_fma_f32 v[74:75], v[140:141], v[74:75], v[80:81]
	v_pk_fma_f32 v[82:83], v[138:139], v[152:153], v[82:83]
	v_pk_fma_f32 v[80:81], v[136:137], v[72:73], v[74:75]
	v_mov_b32_dpp v74, v64 row_ror:1 row_mask:0xf bank_mask:0xf
	v_mov_b32_dpp v72, v64 row_ror:2 row_mask:0xf bank_mask:0xf
	v_mov_b32_dpp v75, v65 row_ror:1 row_mask:0xf bank_mask:0xf
	v_mov_b32_dpp v73, v65 row_ror:2 row_mask:0xf bank_mask:0xf
	v_mov_b32_dpp v154, v66 row_ror:1 row_mask:0xf bank_mask:0xf
	v_mov_b32_dpp v152, v66 row_ror:2 row_mask:0xf bank_mask:0xf
	v_mov_b32_dpp v155, v67 row_ror:1 row_mask:0xf bank_mask:0xf
	v_mov_b32_dpp v153, v67 row_ror:2 row_mask:0xf bank_mask:0xf
	v_cndmask_b32_e64 v18, 0, 1, s[68:69]
	v_mov_b32_dpp v74, v120 row_shr:1 row_mask:0xf bank_mask:0xf
	v_mov_b32_dpp v72, v120 row_shr:2 row_mask:0xf bank_mask:0xf
	v_mov_b32_dpp v75, v121 row_shr:1 row_mask:0xf bank_mask:0xf
	v_mov_b32_dpp v73, v121 row_shr:2 row_mask:0xf bank_mask:0xf
	v_mov_b32_dpp v154, v122 row_shr:1 row_mask:0xf bank_mask:0xf
	v_mov_b32_dpp v152, v122 row_shr:2 row_mask:0xf bank_mask:0xf
	v_mov_b32_dpp v155, v123 row_shr:1 row_mask:0xf bank_mask:0xf
	v_mov_b32_dpp v153, v123 row_shr:2 row_mask:0xf bank_mask:0xf
	v_cmp_ne_u32_e64 s[8:9], 1, v18
	s_andn2_b64 vcc, exec, s[68:69]
	s_mov_b64 s[0:1], -1
	s_cbranch_vccnz .LBB0_1219
	s_mov_b64 s[0:1], 0

; #define LAS __attribute__((address_space(3)))
;     template <int M_> __device__ __forceinline__ f32x4 conv4(const f32x4 c4, const f32x4 pg, const LAS float* bp, int fr, const f32x4 w0, const f32x4 w1, const f32x4 w2, const f32x4 bsv, int db) const {
;         f32x4 p1, p2;
;         if (M_ > 0) {
; #pragma unroll
;             for (int e = 0; e < 4; ++e) { p1[e] = dpp_f<0x111>(dpp_r<0x121>(pg[e]), c4[e]); p2[e] = dpp_f<0x112>(dpp_r<0x122>(pg[e]), c4[e]); }
;         } else {
;             const f32x4 x1 = *(const LAS f32x4*)(bp + 256), x2 = *(const LAS f32x4*)(bp + (fr & 1) * 256);
; #pragma unroll
;             for (int e = 0; e < 4; ++e) { p1[e] = dpp_f<0x111>(x1[e], c4[e]); p2[e] = dpp_f<0x112>(x2[e], c4[e]); }
;         }
;         if ((unsigned)(db + 1) < 17u) { const int d = fr - db;
; #pragma unroll
;             for (int e = 0; e < 4; ++e) { p1[e] = d == 0 ? 0.f : p1[e]; p2[e] = (unsigned)d < 2u ? 0.f : p2[e]; } }
;         f32x4 uu = bsv + w2 * c4 + w1 * p1 + w0 * p2;
;         asm volatile("" : "+v"(uu));
;         return uu;
;     }
;     __device__ __forceinline__ void prompt(f32x4 (&acc)[2][2][4][2], const Unit& u, int row0t, int wr, int wc, int fr, int fq) const {
;     ...
;         for (int step = 0; step < 4; ++step) {
;             const int n = (step == 1 || step == 2) ? 1 : 0, ai = step >> 1;
;             f32x4 w0, w1, w2, bsv;
;             if (step != 2) { const unsigned cso = (unsigned)((DFF + ca + 4 * n) * 4);
;                 w0 = *(const f32x4*)((const char*)cw + cso); w1 = *(const f32x4*)((const char*)(cw + DFF2) + cso); w2 = *(const f32x4*)((const char*)(cw + 2 * DFF2) + cso); bsv = *(const f32x4*)((const char*)cb + cso);
;                 wk[0] = w0; wk[1] = w1; wk[2] = w2; wk[3] = bsv; }
;             else { w0 = wk[0]; w1 = wk[1]; w2 = wk[2]; bsv = wk[3]; }
;             int ps = ai * 2 + wr - 1; ps = ps < 0 ? 0 : ps;
;             const LAS float* bp = bnd + (ps * 2) * 256 + 128 + cl + 4 * n;
;             const int db0 = rho_b - (ai * HALF + wr * 64);
.LBB0_1225:
	v_pk_fma_f32 v[66:67], v[66:67], v[146:147], v[150:151]
	v_pk_fma_f32 v[64:65], v[64:65], v[144:145], v[148:149]
	v_pk_fma_f32 v[66:67], v[142:143], v[154:155], v[66:67]
	v_pk_fma_f32 v[64:65], v[140:141], v[152:153], v[64:65]
	v_pk_fma_f32 v[66:67], v[138:139], v[122:123], v[66:67]
	v_pk_fma_f32 v[64:65], v[136:137], v[120:121], v[64:65]
	v_add_u32_e32 v18, 0x2c00, v175
	global_load_dwordx4 v[148:151], v18, s[54:55]
	global_load_dwordx4 v[152:155], v18, s[34:35]
	global_load_dwordx4 v[120:123], v18, s[96:97]
	global_load_dwordx4 v[156:159], v18, s[66:67]
	v_mov_b32_dpp v138, v108 row_ror:1 row_mask:0xf bank_mask:0xf
	v_mov_b32_dpp v136, v108 row_ror:2 row_mask:0xf bank_mask:0xf
	v_mov_b32_dpp v139, v109 row_ror:1 row_mask:0xf bank_mask:0xf
	v_mov_b32_dpp v137, v109 row_ror:2 row_mask:0xf bank_mask:0xf
	v_mov_b32_dpp v142, v110 row_ror:1 row_mask:0xf bank_mask:0xf
	v_mov_b32_dpp v140, v110 row_ror:2 row_mask:0xf bank_mask:0xf
	v_mov_b32_dpp v143, v111 row_ror:1 row_mask:0xf bank_mask:0xf
	v_mov_b32_dpp v141, v111 row_ror:2 row_mask:0xf bank_mask:0xf
	v_mov_b32_dpp v138, v92 row_shr:1 row_mask:0xf bank_mask:0xf
	v_mov_b32_dpp v136, v92 row_shr:2 row_mask:0xf bank_mask:0xf
	v_mov_b32_dpp v139, v93 row_shr:1 row_mask:0xf bank_mask:0xf
	v_mov_b32_dpp v137, v93 row_shr:2 row_mask:0xf bank_mask:0xf
	v_mov_b32_dpp v142, v94 row_shr:1 row_mask:0xf bank_mask:0xf
	v_mov_b32_dpp v140, v94 row_shr:2 row_mask:0xf bank_mask:0xf
	v_mov_b32_dpp v143, v95 row_shr:1 row_mask:0xf bank_mask:0xf
	v_mov_b32_dpp v141, v95 row_shr:2 row_mask:0xf bank_mask:0xf
	s_and_b64 vcc, exec, s[20:21]
	s_mov_b64 s[0:1], -1
	s_cbranch_vccnz .LBB0_1227
	s_mov_b64 s[0:1], 0

; #define LAS __attribute__((address_space(3)))
;     template <int M_> __device__ __forceinline__ f32x4 conv4(const f32x4 c4, const f32x4 pg, const LAS float* bp, int fr, const f32x4 w0, const f32x4 w1, const f32x4 w2, const f32x4 bsv, int db) const {
;         f32x4 p1, p2;
;         if (M_ > 0) {
; #pragma unroll
;             for (int e = 0; e < 4; ++e) { p1[e] = dpp_f<0x111>(dpp_r<0x121>(pg[e]), c4[e]); p2[e] = dpp_f<0x112>(dpp_r<0x122>(pg[e]), c4[e]); }
;         } else {
;             const f32x4 x1 = *(const LAS f32x4*)(bp + 256), x2 = *(const LAS f32x4*)(bp + (fr & 1) * 256);
; #pragma unroll
;             for (int e = 0; e < 4; ++e) { p1[e] = dpp_f<0x111>(x1[e], c4[e]); p2[e] = dpp_f<0x112>(x2[e], c4[e]); }
;         }
;         if ((unsigned)(db + 1) < 17u) { const int d = fr - db;
; #pragma unroll
;             for (int e = 0; e < 4; ++e) { p1[e] = d == 0 ? 0.f : p1[e]; p2[e] = (unsigned)d < 2u ? 0.f : p2[e]; } }
;         f32x4 uu = bsv + w2 * c4 + w1 * p1 + w0 * p2;
;         asm volatile("" : "+v"(uu));
;         return uu;
;     }
;     __device__ __forceinline__ void prompt(f32x4 (&acc)[2][2][4][2], const Unit& u, int row0t, int wr, int wc, int fr, int fq) const {
;     ...
;         for (int step = 0; step < 4; ++step) {
;             const int n = (step == 1 || step == 2) ? 1 : 0, ai = step >> 1;
;             f32x4 w0, w1, w2, bsv;
;             if (step != 2) { const unsigned cso = (unsigned)((DFF + ca + 4 * n) * 4);
;                 w0 = *(const f32x4*)((const char*)cw + cso); w1 = *(const f32x4*)((const char*)(cw + DFF2) + cso); w2 = *(const f32x4*)((const char*)(cw + 2 * DFF2) + cso); bsv = *(const f32x4*)((const char*)cb + cso);
;                 wk[0] = w0; wk[1] = w1; wk[2] = w2; wk[3] = bsv; }
;             else { w0 = wk[0]; w1 = wk[1]; w2 = wk[2]; bsv = wk[3]; }
;             int ps = ai * 2 + wr - 1; ps = ps < 0 ? 0 : ps;
;             const LAS float* bp = bnd + (ps * 2) * 256 + 128 + cl + 4 * n;
;             const int db0 = rho_b - (ai * HALF + wr * 64);
;     ...
;             FFN_GATE_STORE(3); FFN_GATE_STORE(2); FFN_GATE_STORE(1); FFN_GATE_STORE(0);
.LBB0_1229:
	s_waitcnt vmcnt(0)
	v_pk_fma_f32 v[94:95], v[94:95], v[154:155], v[158:159]
	v_pk_fma_f32 v[92:93], v[92:93], v[152:153], v[156:157]
	v_pk_fma_f32 v[94:95], v[150:151], v[142:143], v[94:95]
	v_pk_fma_f32 v[92:93], v[148:149], v[138:139], v[92:93]
	v_pk_fma_f32 v[146:147], v[122:123], v[140:141], v[94:95]
	v_pk_fma_f32 v[144:145], v[120:121], v[136:137], v[92:93]
	s_nop 0
	v_mov_b32_dpp v94, v96 row_ror:1 row_mask:0xf bank_mask:0xf
	v_mov_b32_dpp v92, v96 row_ror:2 row_mask:0xf bank_mask:0xf
	v_mov_b32_dpp v95, v97 row_ror:1 row_mask:0xf bank_mask:0xf
	v_mov_b32_dpp v93, v97 row_ror:2 row_mask:0xf bank_mask:0xf
	v_mov_b32_dpp v138, v98 row_ror:1 row_mask:0xf bank_mask:0xf
	v_mov_b32_dpp v136, v98 row_ror:2 row_mask:0xf bank_mask:0xf
	v_mov_b32_dpp v139, v99 row_ror:1 row_mask:0xf bank_mask:0xf
	v_mov_b32_dpp v137, v99 row_ror:2 row_mask:0xf bank_mask:0xf
	v_mov_b32_dpp v94, v108 row_shr:1 row_mask:0xf bank_mask:0xf
	v_mov_b32_dpp v92, v108 row_shr:2 row_mask:0xf bank_mask:0xf
	v_mov_b32_dpp v95, v109 row_shr:1 row_mask:0xf bank_mask:0xf
	v_mov_b32_dpp v93, v109 row_shr:2 row_mask:0xf bank_mask:0xf
	v_mov_b32_dpp v138, v110 row_shr:1 row_mask:0xf bank_mask:0xf
	v_mov_b32_dpp v136, v110 row_shr:2 row_mask:0xf bank_mask:0xf
	v_mov_b32_dpp v139, v111 row_shr:1 row_mask:0xf bank_mask:0xf
	v_mov_b32_dpp v137, v111 row_shr:2 row_mask:0xf bank_mask:0xf
	s_and_b64 vcc, exec, s[18:19]
	s_mov_b64 s[0:1], -1
	s_cbranch_vccnz .LBB0_1231
	s_mov_b64 s[0:1], 0

; #define LAS __attribute__((address_space(3)))
;     template <int M_> __device__ __forceinline__ f32x4 conv4(const f32x4 c4, const f32x4 pg, const LAS float* bp, int fr, const f32x4 w0, const f32x4 w1, const f32x4 w2, const f32x4 bsv, int db) const {
;         f32x4 p1, p2;
;         if (M_ > 0) {
; #pragma unroll
;             for (int e = 0; e < 4; ++e) { p1[e] = dpp_f<0x111>(dpp_r<0x121>(pg[e]), c4[e]); p2[e] = dpp_f<0x112>(dpp_r<0x122>(pg[e]), c4[e]); }
;         } else {
;             const f32x4 x1 = *(const LAS f32x4*)(bp + 256), x2 = *(const LAS f32x4*)(bp + (fr & 1) * 256);
; #pragma unroll
;             for (int e = 0; e < 4; ++e) { p1[e] = dpp_f<0x111>(x1[e], c4[e]); p2[e] = dpp_f<0x112>(x2[e], c4[e]); }
;         }
;         if ((unsigned)(db + 1) < 17u) { const int d = fr - db;
; #pragma unroll
;             for (int e = 0; e < 4; ++e) { p1[e] = d == 0 ? 0.f : p1[e]; p2[e] = (unsigned)d < 2u ? 0.f : p2[e]; } }
;         f32x4 uu = bsv + w2 * c4 + w1 * p1 + w0 * p2;
;         asm volatile("" : "+v"(uu));
;         return uu;
;     }
;     __device__ __forceinline__ void prompt(f32x4 (&acc)[2][2][4][2], const Unit& u, int row0t, int wr, int wc, int fr, int fq) const {
;     ...
;         for (int step = 0; step < 4; ++step) {
;             const int n = (step == 1 || step == 2) ? 1 : 0, ai = step >> 1;
;             f32x4 w0, w1, w2, bsv;
;             if (step != 2) { const unsigned cso = (unsigned)((DFF + ca + 4 * n) * 4);
;                 w0 = *(const f32x4*)((const char*)cw + cso); w1 = *(const f32x4*)((const char*)(cw + DFF2) + cso); w2 = *(const f32x4*)((const char*)(cw + 2 * DFF2) + cso); bsv = *(const f32x4*)((const char*)cb + cso);
;                 wk[0] = w0; wk[1] = w1; wk[2] = w2; wk[3] = bsv; }
;             else { w0 = wk[0]; w1 = wk[1]; w2 = wk[2]; bsv = wk[3]; }
;             int ps = ai * 2 + wr - 1; ps = ps < 0 ? 0 : ps;
;             const LAS float* bp = bnd + (ps * 2) * 256 + 128 + cl + 4 * n;
;             const int db0 = rho_b - (ai * HALF + wr * 64);
;     ...
;             FFN_GATE_STORE(3); FFN_GATE_STORE(2); FFN_GATE_STORE(1); FFN_GATE_STORE(0);
.LBB0_1233:
	v_pk_fma_f32 v[110:111], v[110:111], v[154:155], v[158:159]
	v_pk_fma_f32 v[108:109], v[108:109], v[152:153], v[156:157]
	v_pk_fma_f32 v[110:111], v[150:151], v[138:139], v[110:111]
	v_pk_fma_f32 v[94:95], v[148:149], v[94:95], v[108:109]
	v_pk_fma_f32 v[142:143], v[122:123], v[136:137], v[110:111]
	v_pk_fma_f32 v[140:141], v[120:121], v[92:93], v[94:95]
	s_nop 0
	v_mov_b32_dpp v94, v84 row_ror:1 row_mask:0xf bank_mask:0xf
	v_mov_b32_dpp v92, v84 row_ror:2 row_mask:0xf bank_mask:0xf
	v_mov_b32_dpp v95, v85 row_ror:1 row_mask:0xf bank_mask:0xf
	v_mov_b32_dpp v93, v85 row_ror:2 row_mask:0xf bank_mask:0xf
	v_mov_b32_dpp v110, v86 row_ror:1 row_mask:0xf bank_mask:0xf
	v_mov_b32_dpp v108, v86 row_ror:2 row_mask:0xf bank_mask:0xf
	v_mov_b32_dpp v111, v87 row_ror:1 row_mask:0xf bank_mask:0xf
	v_mov_b32_dpp v109, v87 row_ror:2 row_mask:0xf bank_mask:0xf
	v_mov_b32_dpp v94, v96 row_shr:1 row_mask:0xf bank_mask:0xf
	v_mov_b32_dpp v92, v96 row_shr:2 row_mask:0xf bank_mask:0xf
	v_mov_b32_dpp v95, v97 row_shr:1 row_mask:0xf bank_mask:0xf
	v_mov_b32_dpp v93, v97 row_shr:2 row_mask:0xf bank_mask:0xf
	v_mov_b32_dpp v110, v98 row_shr:1 row_mask:0xf bank_mask:0xf
	v_mov_b32_dpp v108, v98 row_shr:2 row_mask:0xf bank_mask:0xf
	v_mov_b32_dpp v111, v99 row_shr:1 row_mask:0xf bank_mask:0xf
	v_mov_b32_dpp v109, v99 row_shr:2 row_mask:0xf bank_mask:0xf
	s_and_b64 vcc, exec, s[16:17]
	s_mov_b64 s[0:1], -1
	s_cbranch_vccnz .LBB0_1235
	s_mov_b64 s[0:1], 0

; #define LAS __attribute__((address_space(3)))
;     template <int M_> __device__ __forceinline__ f32x4 conv4(const f32x4 c4, const f32x4 pg, const LAS float* bp, int fr, const f32x4 w0, const f32x4 w1, const f32x4 w2, const f32x4 bsv, int db) const {
;         f32x4 p1, p2;
;         if (M_ > 0) {
; #pragma unroll
;             for (int e = 0; e < 4; ++e) { p1[e] = dpp_f<0x111>(dpp_r<0x121>(pg[e]), c4[e]); p2[e] = dpp_f<0x112>(dpp_r<0x122>(pg[e]), c4[e]); }
;         } else {
;             const f32x4 x1 = *(const LAS f32x4*)(bp + 256), x2 = *(const LAS f32x4*)(bp + (fr & 1) * 256);
; #pragma unroll
;             for (int e = 0; e < 4; ++e) { p1[e] = dpp_f<0x111>(x1[e], c4[e]); p2[e] = dpp_f<0x112>(x2[e], c4[e]); }
;         }
;         if ((unsigned)(db + 1) < 17u) { const int d = fr - db;
; #pragma unroll
;             for (int e = 0; e < 4; ++e) { p1[e] = d == 0 ? 0.f : p1[e]; p2[e] = (unsigned)d < 2u ? 0.f : p2[e]; } }
;         f32x4 uu = bsv + w2 * c4 + w1 * p1 + w0 * p2;
;         asm volatile("" : "+v"(uu));
;         return uu;
;     }
;     __device__ __forceinline__ void prompt(f32x4 (&acc)[2][2][4][2], const Unit& u, int row0t, int wr, int wc, int fr, int fq) const {
;     ...
;         for (int step = 0; step < 4; ++step) {
;             const int n = (step == 1 || step == 2) ? 1 : 0, ai = step >> 1;
;             f32x4 w0, w1, w2, bsv;
;             if (step != 2) { const unsigned cso = (unsigned)((DFF + ca + 4 * n) * 4);
;                 w0 = *(const f32x4*)((const char*)cw + cso); w1 = *(const f32x4*)((const char*)(cw + DFF2) + cso); w2 = *(const f32x4*)((const char*)(cw + 2 * DFF2) + cso); bsv = *(const f32x4*)((const char*)cb + cso);
;                 wk[0] = w0; wk[1] = w1; wk[2] = w2; wk[3] = bsv; }
;             else { w0 = wk[0]; w1 = wk[1]; w2 = wk[2]; bsv = wk[3]; }
;             int ps = ai * 2 + wr - 1; ps = ps < 0 ? 0 : ps;
;             const LAS float* bp = bnd + (ps * 2) * 256 + 128 + cl + 4 * n;
;             const int db0 = rho_b - (ai * HALF + wr * 64);
;     ...
;             FFN_GATE_STORE(3); FFN_GATE_STORE(2); FFN_GATE_STORE(1); FFN_GATE_STORE(0);
.LBB0_1241:
	v_pk_fma_f32 v[86:87], v[86:87], v[154:155], v[158:159]
	v_pk_fma_f32 v[84:85], v[84:85], v[152:153], v[156:157]
	v_pk_fma_f32 v[86:87], v[150:151], v[98:99], v[86:87]
	v_pk_fma_f32 v[84:85], v[148:149], v[96:97], v[84:85]
	v_pk_fma_f32 v[122:123], v[122:123], v[94:95], v[86:87]
	v_pk_fma_f32 v[120:121], v[120:121], v[92:93], v[84:85]
	s_nop 0
	v_add_u32_e32 v108, 0x2c10, v175
	global_load_dwordx4 v[92:95], v108, s[54:55]
	global_load_dwordx4 v[96:99], v108, s[34:35]
	global_load_dwordx4 v[84:87], v108, s[96:97]
	s_nop 0
	global_load_dwordx4 v[108:111], v108, s[66:67]
	v_mov_b32_dpp v150, v68 row_ror:1 row_mask:0xf bank_mask:0xf
	v_mov_b32_dpp v148, v68 row_ror:2 row_mask:0xf bank_mask:0xf
	v_mov_b32_dpp v151, v69 row_ror:1 row_mask:0xf bank_mask:0xf
	v_mov_b32_dpp v149, v69 row_ror:2 row_mask:0xf bank_mask:0xf
	v_mov_b32_dpp v154, v70 row_ror:1 row_mask:0xf bank_mask:0xf
	v_mov_b32_dpp v152, v70 row_ror:2 row_mask:0xf bank_mask:0xf
	v_mov_b32_dpp v155, v71 row_ror:1 row_mask:0xf bank_mask:0xf
	v_mov_b32_dpp v153, v71 row_ror:2 row_mask:0xf bank_mask:0xf
	v_mov_b32_dpp v150, v60 row_shr:1 row_mask:0xf bank_mask:0xf
	v_mov_b32_dpp v148, v60 row_shr:2 row_mask:0xf bank_mask:0xf
	v_mov_b32_dpp v151, v61 row_shr:1 row_mask:0xf bank_mask:0xf
	v_mov_b32_dpp v149, v61 row_shr:2 row_mask:0xf bank_mask:0xf
	v_mov_b32_dpp v154, v62 row_shr:1 row_mask:0xf bank_mask:0xf
	v_mov_b32_dpp v152, v62 row_shr:2 row_mask:0xf bank_mask:0xf
	v_mov_b32_dpp v155, v63 row_shr:1 row_mask:0xf bank_mask:0xf
	v_mov_b32_dpp v153, v63 row_shr:2 row_mask:0xf bank_mask:0xf
	s_and_b64 vcc, exec, s[20:21]
	s_mov_b64 s[0:1], -1
	s_cbranch_vccnz .LBB0_1243
	s_mov_b64 s[0:1], 0

;     __device__ __forceinline__ void prompt(f32x4 (&acc)[2][2][4][2], const Unit& u, int row0t, int wr, int wc, int fr, int fq) const {
;     ...
;             FFN_GATE_STORE(3); FFN_GATE_STORE(2); FFN_GATE_STORE(1); FFN_GATE_STORE(0);
.LBB0_1245:
	v_mul_f32_e32 v156, 0xbfb8aa3b, v114
	v_mul_f32_e32 v157, 0xbfb8aa3b, v115
	v_exp_f32_e32 v156, v156
	v_exp_f32_e32 v157, v157
	s_waitcnt vmcnt(0)
	v_pk_fma_f32 v[62:63], v[62:63], v[98:99], v[110:111]
	v_pk_fma_f32 v[60:61], v[60:61], v[96:97], v[108:109]
	v_add_f32_e32 v156, 1.0, v156
	v_add_f32_e32 v157, 1.0, v157
	v_rcp_f32_e32 v156, v156
	v_rcp_f32_e32 v157, v157
	v_pk_fma_f32 v[62:63], v[94:95], v[154:155], v[62:63]
	v_pk_fma_f32 v[60:61], v[92:93], v[150:151], v[60:61]
	v_pk_fma_f32 v[62:63], v[86:87], v[152:153], v[62:63]
	v_pk_mul_f32 v[114:115], v[114:115], v[156:157]
	v_pk_fma_f32 v[60:61], v[84:85], v[148:149], v[60:61]
	v_pk_mul_f32 v[114:115], v[114:115], v[146:147]
	s_movk_i32 s0, 0x1600
	v_cvt_pk_bf16_f32 v157, v114, v115
	v_mul_f32_e32 v114, 0xbfb8aa3b, v112
	v_mul_f32_e32 v115, 0xbfb8aa3b, v113
	v_exp_f32_e32 v114, v114
	v_exp_f32_e32 v115, v115
	v_lshlrev_b32_e32 v146, 1, v174
	v_add_f32_e32 v114, 1.0, v114
	v_add_f32_e32 v115, 1.0, v115
	v_rcp_f32_e32 v114, v114
	v_rcp_f32_e32 v115, v115
	s_nop 0
	v_pk_mul_f32 v[112:113], v[112:113], v[114:115]
	s_nop 0
	v_pk_mul_f32 v[112:113], v[112:113], v[144:145]
	v_mul_lo_u32 v145, v172, s0
	v_cvt_pk_bf16_f32 v156, v112, v113
	v_mul_f32_e32 v112, 0xbfb8aa3b, v134
	v_mul_f32_e32 v113, 0xbfb8aa3b, v135
	v_exp_f32_e32 v112, v112
	v_exp_f32_e32 v113, v113
	s_mov_b32 s0, 0x42000
	v_add3_u32 v144, v145, v146, s0
	v_add_f32_e32 v112, 1.0, v112
	v_add_f32_e32 v113, 1.0, v113
	v_rcp_f32_e32 v112, v112
	v_rcp_f32_e32 v113, v113
	s_nop 0
	v_pk_mul_f32 v[112:113], v[134:135], v[112:113]
	s_nop 0
	v_pk_mul_f32 v[62:63], v[112:113], v[62:63]
	s_nop 0
	v_cvt_pk_bf16_f32 v159, v62, v63
	v_mul_f32_e32 v62, 0xbfb8aa3b, v132
	v_mul_f32_e32 v63, 0xbfb8aa3b, v133
	v_exp_f32_e32 v62, v62
	v_exp_f32_e32 v63, v63
	v_add_f32_e32 v62, 1.0, v62
	v_add_f32_e32 v63, 1.0, v63
	v_rcp_f32_e32 v62, v62
	v_rcp_f32_e32 v63, v63
	s_nop 0
	v_pk_mul_f32 v[62:63], v[132:133], v[62:63]
	s_nop 0
	v_pk_mul_f32 v[60:61], v[62:63], v[60:61]
	s_nop 0
	v_cvt_pk_bf16_f32 v158, v60, v61
	global_store_dwordx4 v144, v[156:159], s[70:71]
	v_mov_b32_dpp v62, v56 row_ror:1 row_mask:0xf bank_mask:0xf
	v_mov_b32_dpp v60, v56 row_ror:2 row_mask:0xf bank_mask:0xf
	v_mov_b32_dpp v63, v57 row_ror:1 row_mask:0xf bank_mask:0xf
	v_mov_b32_dpp v61, v57 row_ror:2 row_mask:0xf bank_mask:0xf
	v_mov_b32_dpp v114, v58 row_ror:1 row_mask:0xf bank_mask:0xf
	v_mov_b32_dpp v112, v58 row_ror:2 row_mask:0xf bank_mask:0xf
	v_mov_b32_dpp v115, v59 row_ror:1 row_mask:0xf bank_mask:0xf
	v_mov_b32_dpp v113, v59 row_ror:2 row_mask:0xf bank_mask:0xf
	v_mov_b32_dpp v62, v68 row_shr:1 row_mask:0xf bank_mask:0xf
	v_mov_b32_dpp v60, v68 row_shr:2 row_mask:0xf bank_mask:0xf
	v_mov_b32_dpp v63, v69 row_shr:1 row_mask:0xf bank_mask:0xf
	v_mov_b32_dpp v61, v69 row_shr:2 row_mask:0xf bank_mask:0xf
	v_mov_b32_dpp v114, v70 row_shr:1 row_mask:0xf bank_mask:0xf
	v_mov_b32_dpp v112, v70 row_shr:2 row_mask:0xf bank_mask:0xf
	v_mov_b32_dpp v115, v71 row_shr:1 row_mask:0xf bank_mask:0xf
	v_mov_b32_dpp v113, v71 row_shr:2 row_mask:0xf bank_mask:0xf
	s_and_b64 vcc, exec, s[18:19]
	s_mov_b64 s[0:1], -1
	s_cbranch_vccnz .LBB0_1247
	s_mov_b64 s[0:1], 0

;     __device__ __forceinline__ void prompt(f32x4 (&acc)[2][2][4][2], const Unit& u, int row0t, int wr, int wc, int fr, int fq) const {
;     ...
;             FFN_GATE_STORE(3); FFN_GATE_STORE(2); FFN_GATE_STORE(1); FFN_GATE_STORE(0);
.LBB0_1249:
	v_pk_fma_f32 v[68:69], v[68:69], v[96:97], v[108:109]
	v_mul_f32_e32 v132, 0xbfb8aa3b, v106
	v_pk_fma_f32 v[68:69], v[92:93], v[62:63], v[68:69]
	v_mul_f32_e32 v133, 0xbfb8aa3b, v107
	v_pk_fma_f32 v[60:61], v[84:85], v[60:61], v[68:69]
	v_mul_f32_e32 v68, 0xbfb8aa3b, v130
	v_mul_f32_e32 v69, 0xbfb8aa3b, v131
	v_exp_f32_e32 v132, v132
	v_exp_f32_e32 v133, v133
	v_exp_f32_e32 v68, v68
	v_exp_f32_e32 v69, v69
	v_add_f32_e32 v132, 1.0, v132
	v_add_f32_e32 v133, 1.0, v133
	v_add_f32_e32 v68, 1.0, v68
	v_add_f32_e32 v69, 1.0, v69
	v_rcp_f32_e32 v132, v132
	v_rcp_f32_e32 v133, v133
	v_rcp_f32_e32 v68, v68
	v_rcp_f32_e32 v69, v69
	v_pk_fma_f32 v[70:71], v[70:71], v[98:99], v[110:111]
	v_pk_mul_f32 v[106:107], v[106:107], v[132:133]
	v_pk_fma_f32 v[70:71], v[94:95], v[114:115], v[70:71]
	v_pk_mul_f32 v[68:69], v[130:131], v[68:69]
	v_pk_fma_f32 v[62:63], v[86:87], v[112:113], v[70:71]
	v_pk_mul_f32 v[106:107], v[106:107], v[142:143]
	s_mov_b32 s0, 0x2c000
	v_pk_mul_f32 v[62:63], v[68:69], v[62:63]
	v_cvt_pk_bf16_f32 v133, v106, v107
	v_mul_f32_e32 v106, 0xbfb8aa3b, v104
	v_mul_f32_e32 v107, 0xbfb8aa3b, v105
	v_cvt_pk_bf16_f32 v135, v62, v63
	v_mul_f32_e32 v62, 0xbfb8aa3b, v128
	v_mul_f32_e32 v63, 0xbfb8aa3b, v129
	v_exp_f32_e32 v106, v106
	v_exp_f32_e32 v107, v107
	v_exp_f32_e32 v62, v62
	v_exp_f32_e32 v63, v63
	v_add_f32_e32 v106, 1.0, v106
	v_add_f32_e32 v107, 1.0, v107
	v_add_f32_e32 v62, 1.0, v62
	v_add_f32_e32 v63, 1.0, v63
	v_rcp_f32_e32 v106, v106
	v_rcp_f32_e32 v107, v107
	v_rcp_f32_e32 v62, v62
	v_rcp_f32_e32 v63, v63
	v_pk_mul_f32 v[104:105], v[104:105], v[106:107]
	s_nop 0
	v_pk_mul_f32 v[104:105], v[104:105], v[140:141]
	v_pk_mul_f32 v[62:63], v[128:129], v[62:63]
	v_cvt_pk_bf16_f32 v132, v104, v105
	v_pk_mul_f32 v[60:61], v[62:63], v[60:61]
	v_add3_u32 v104, v145, v146, s0
	v_cvt_pk_bf16_f32 v134, v60, v61
	global_store_dwordx4 v104, v[132:135], s[70:71]
	v_mov_b32_dpp v62, v48 row_ror:1 row_mask:0xf bank_mask:0xf
	v_mov_b32_dpp v60, v48 row_ror:2 row_mask:0xf bank_mask:0xf
	v_mov_b32_dpp v63, v49 row_ror:1 row_mask:0xf bank_mask:0xf
	v_mov_b32_dpp v61, v49 row_ror:2 row_mask:0xf bank_mask:0xf
	v_mov_b32_dpp v70, v50 row_ror:1 row_mask:0xf bank_mask:0xf
	v_mov_b32_dpp v68, v50 row_ror:2 row_mask:0xf bank_mask:0xf
	v_mov_b32_dpp v71, v51 row_ror:1 row_mask:0xf bank_mask:0xf
	v_mov_b32_dpp v69, v51 row_ror:2 row_mask:0xf bank_mask:0xf
	v_mov_b32_dpp v62, v56 row_shr:1 row_mask:0xf bank_mask:0xf
	v_mov_b32_dpp v60, v56 row_shr:2 row_mask:0xf bank_mask:0xf
	v_mov_b32_dpp v63, v57 row_shr:1 row_mask:0xf bank_mask:0xf
	v_mov_b32_dpp v61, v57 row_shr:2 row_mask:0xf bank_mask:0xf
	v_mov_b32_dpp v70, v58 row_shr:1 row_mask:0xf bank_mask:0xf
	v_mov_b32_dpp v68, v58 row_shr:2 row_mask:0xf bank_mask:0xf
	v_mov_b32_dpp v71, v59 row_shr:1 row_mask:0xf bank_mask:0xf
	v_mov_b32_dpp v69, v59 row_shr:2 row_mask:0xf bank_mask:0xf
	s_and_b64 vcc, exec, s[16:17]
	s_mov_b64 s[0:1], -1
	s_cbranch_vccnz .LBB0_1251
	s_mov_b64 s[0:1], 0

; #define LAS __attribute__((address_space(3)))
;     template <int M_> __device__ __forceinline__ f32x4 conv4(const f32x4 c4, const f32x4 pg, const LAS float* bp, int fr, const f32x4 w0, const f32x4 w1, const f32x4 w2, const f32x4 bsv, int db) const {
;         f32x4 p1, p2;
;         if (M_ > 0) {
; #pragma unroll
;             for (int e = 0; e < 4; ++e) { p1[e] = dpp_f<0x111>(dpp_r<0x121>(pg[e]), c4[e]); p2[e] = dpp_f<0x112>(dpp_r<0x122>(pg[e]), c4[e]); }
;         } else {
;             const f32x4 x1 = *(const LAS f32x4*)(bp + 256), x2 = *(const LAS f32x4*)(bp + (fr & 1) * 256);
; #pragma unroll
;             for (int e = 0; e < 4; ++e) { p1[e] = dpp_f<0x111>(x1[e], c4[e]); p2[e] = dpp_f<0x112>(x2[e], c4[e]); }
;         }
.LBB0_1259:
	s_or_b64 exec, exec, s[0:1]
	v_mov_b32_dpp v50, v40 row_ror:1 row_mask:0xf bank_mask:0xf
	v_mov_b32_dpp v48, v40 row_ror:2 row_mask:0xf bank_mask:0xf
	v_mov_b32_dpp v51, v41 row_ror:1 row_mask:0xf bank_mask:0xf
	v_mov_b32_dpp v49, v41 row_ror:2 row_mask:0xf bank_mask:0xf
	v_mov_b32_dpp v58, v42 row_ror:1 row_mask:0xf bank_mask:0xf
	v_mov_b32_dpp v56, v42 row_ror:2 row_mask:0xf bank_mask:0xf
	v_mov_b32_dpp v59, v43 row_ror:1 row_mask:0xf bank_mask:0xf
	v_mov_b32_dpp v57, v43 row_ror:2 row_mask:0xf bank_mask:0xf
	v_mov_b32_dpp v50, v28 row_shr:1 row_mask:0xf bank_mask:0xf
	v_mov_b32_dpp v48, v28 row_shr:2 row_mask:0xf bank_mask:0xf
	v_mov_b32_dpp v51, v29 row_shr:1 row_mask:0xf bank_mask:0xf
	v_mov_b32_dpp v49, v29 row_shr:2 row_mask:0xf bank_mask:0xf
	v_mov_b32_dpp v58, v30 row_shr:1 row_mask:0xf bank_mask:0xf
	v_mov_b32_dpp v56, v30 row_shr:2 row_mask:0xf bank_mask:0xf
	v_mov_b32_dpp v59, v31 row_shr:1 row_mask:0xf bank_mask:0xf
	v_mov_b32_dpp v57, v31 row_shr:2 row_mask:0xf bank_mask:0xf
	s_and_b64 vcc, exec, s[12:13]
	s_mov_b64 s[0:1], -1
	s_cbranch_vccnz .LBB0_1261
	s_mov_b64 s[0:1], 0

; #define LAS __attribute__((address_space(3)))
;     template <int M_> __device__ __forceinline__ f32x4 conv4(const f32x4 c4, const f32x4 pg, const LAS float* bp, int fr, const f32x4 w0, const f32x4 w1, const f32x4 w2, const f32x4 bsv, int db) const {
;         f32x4 p1, p2;
;         if (M_ > 0) {
; #pragma unroll
;             for (int e = 0; e < 4; ++e) { p1[e] = dpp_f<0x111>(dpp_r<0x121>(pg[e]), c4[e]); p2[e] = dpp_f<0x112>(dpp_r<0x122>(pg[e]), c4[e]); }
;         } else {
;             const f32x4 x1 = *(const LAS f32x4*)(bp + 256), x2 = *(const LAS f32x4*)(bp + (fr & 1) * 256);
; #pragma unroll
;             for (int e = 0; e < 4; ++e) { p1[e] = dpp_f<0x111>(x1[e], c4[e]); p2[e] = dpp_f<0x112>(x2[e], c4[e]); }
;         }
;         if ((unsigned)(db + 1) < 17u) { const int d = fr - db;
; #pragma unroll
;             for (int e = 0; e < 4; ++e) { p1[e] = d == 0 ? 0.f : p1[e]; p2[e] = (unsigned)d < 2u ? 0.f : p2[e]; } }
;         f32x4 uu = bsv + w2 * c4 + w1 * p1 + w0 * p2;
;         asm volatile("" : "+v"(uu));
;         return uu;
;     }
;     __device__ __forceinline__ void prompt(f32x4 (&acc)[2][2][4][2], const Unit& u, int row0t, int wr, int wc, int fr, int fq) const {
;     ...
;             FFN_GATE_STORE(3); FFN_GATE_STORE(2); FFN_GATE_STORE(1); FFN_GATE_STORE(0);
.LBB0_1263:
	v_pk_fma_f32 v[30:31], v[30:31], v[98:99], v[110:111]
	v_pk_fma_f32 v[28:29], v[28:29], v[96:97], v[108:109]
	v_pk_fma_f32 v[30:31], v[94:95], v[58:59], v[30:31]
	v_pk_fma_f32 v[28:29], v[92:93], v[50:51], v[28:29]
	v_pk_fma_f32 v[70:71], v[86:87], v[56:57], v[30:31]
	v_pk_fma_f32 v[68:69], v[84:85], v[48:49], v[28:29]
	s_nop 0
	v_mov_b32_dpp v30, v32 row_ror:1 row_mask:0xf bank_mask:0xf
	v_mov_b32_dpp v28, v32 row_ror:2 row_mask:0xf bank_mask:0xf
	v_mov_b32_dpp v31, v33 row_ror:1 row_mask:0xf bank_mask:0xf
	v_mov_b32_dpp v29, v33 row_ror:2 row_mask:0xf bank_mask:0xf
	v_mov_b32_dpp v50, v34 row_ror:1 row_mask:0xf bank_mask:0xf
	v_mov_b32_dpp v48, v34 row_ror:2 row_mask:0xf bank_mask:0xf
	v_mov_b32_dpp v51, v35 row_ror:1 row_mask:0xf bank_mask:0xf
	v_mov_b32_dpp v49, v35 row_ror:2 row_mask:0xf bank_mask:0xf
	v_mov_b32_dpp v30, v40 row_shr:1 row_mask:0xf bank_mask:0xf
	v_mov_b32_dpp v28, v40 row_shr:2 row_mask:0xf bank_mask:0xf
	v_mov_b32_dpp v31, v41 row_shr:1 row_mask:0xf bank_mask:0xf
	v_mov_b32_dpp v29, v41 row_shr:2 row_mask:0xf bank_mask:0xf
	v_mov_b32_dpp v50, v42 row_shr:1 row_mask:0xf bank_mask:0xf
	v_mov_b32_dpp v48, v42 row_shr:2 row_mask:0xf bank_mask:0xf
	v_mov_b32_dpp v51, v43 row_shr:1 row_mask:0xf bank_mask:0xf
	v_mov_b32_dpp v49, v43 row_shr:2 row_mask:0xf bank_mask:0xf
	s_and_b64 vcc, exec, s[10:11]
	s_mov_b64 s[0:1], -1
	s_cbranch_vccnz .LBB0_1265
	s_mov_b64 s[0:1], 0

; #define LAS __attribute__((address_space(3)))
;     template <int M_> __device__ __forceinline__ f32x4 conv4(const f32x4 c4, const f32x4 pg, const LAS float* bp, int fr, const f32x4 w0, const f32x4 w1, const f32x4 w2, const f32x4 bsv, int db) const {
;         f32x4 p1, p2;
;         if (M_ > 0) {
; #pragma unroll
;             for (int e = 0; e < 4; ++e) { p1[e] = dpp_f<0x111>(dpp_r<0x121>(pg[e]), c4[e]); p2[e] = dpp_f<0x112>(dpp_r<0x122>(pg[e]), c4[e]); }
;         } else {
;             const f32x4 x1 = *(const LAS f32x4*)(bp + 256), x2 = *(const LAS f32x4*)(bp + (fr & 1) * 256);
; #pragma unroll
;             for (int e = 0; e < 4; ++e) { p1[e] = dpp_f<0x111>(x1[e], c4[e]); p2[e] = dpp_f<0x112>(x2[e], c4[e]); }
;         }
;         if ((unsigned)(db + 1) < 17u) { const int d = fr - db;
; #pragma unroll
;             for (int e = 0; e < 4; ++e) { p1[e] = d == 0 ? 0.f : p1[e]; p2[e] = (unsigned)d < 2u ? 0.f : p2[e]; } }
;         f32x4 uu = bsv + w2 * c4 + w1 * p1 + w0 * p2;
;         asm volatile("" : "+v"(uu));
;         return uu;
;     }
;     __device__ __forceinline__ void prompt(f32x4 (&acc)[2][2][4][2], const Unit& u, int row0t, int wr, int wc, int fr, int fq) const {
;     ...
;             FFN_GATE_STORE(3); FFN_GATE_STORE(2); FFN_GATE_STORE(1); FFN_GATE_STORE(0);
.LBB0_1267:
	v_pk_fma_f32 v[42:43], v[42:43], v[98:99], v[110:111]
	v_pk_fma_f32 v[40:41], v[40:41], v[96:97], v[108:109]
	v_pk_fma_f32 v[42:43], v[94:95], v[50:51], v[42:43]
	v_pk_fma_f32 v[30:31], v[92:93], v[30:31], v[40:41]
	v_pk_fma_f32 v[62:63], v[86:87], v[48:49], v[42:43]
	v_pk_fma_f32 v[60:61], v[84:85], v[28:29], v[30:31]
	s_nop 0
	v_mov_b32_dpp v30, v20 row_ror:1 row_mask:0xf bank_mask:0xf
	v_mov_b32_dpp v28, v20 row_ror:2 row_mask:0xf bank_mask:0xf
	v_mov_b32_dpp v31, v21 row_ror:1 row_mask:0xf bank_mask:0xf
	v_mov_b32_dpp v29, v21 row_ror:2 row_mask:0xf bank_mask:0xf
	v_mov_b32_dpp v42, v22 row_ror:1 row_mask:0xf bank_mask:0xf
	v_mov_b32_dpp v40, v22 row_ror:2 row_mask:0xf bank_mask:0xf
	v_mov_b32_dpp v43, v23 row_ror:1 row_mask:0xf bank_mask:0xf
	v_mov_b32_dpp v41, v23 row_ror:2 row_mask:0xf bank_mask:0xf
	v_mov_b32_dpp v30, v32 row_shr:1 row_mask:0xf bank_mask:0xf
	v_mov_b32_dpp v28, v32 row_shr:2 row_mask:0xf bank_mask:0xf
	v_mov_b32_dpp v31, v33 row_shr:1 row_mask:0xf bank_mask:0xf
	v_mov_b32_dpp v29, v33 row_shr:2 row_mask:0xf bank_mask:0xf
	v_mov_b32_dpp v42, v34 row_shr:1 row_mask:0xf bank_mask:0xf
	v_mov_b32_dpp v40, v34 row_shr:2 row_mask:0xf bank_mask:0xf
	v_mov_b32_dpp v43, v35 row_shr:1 row_mask:0xf bank_mask:0xf
	v_mov_b32_dpp v41, v35 row_shr:2 row_mask:0xf bank_mask:0xf
	s_and_b64 vcc, exec, s[8:9]
	s_mov_b64 s[0:1], -1
	s_cbranch_vccnz .LBB0_1269
	s_mov_b64 s[0:1], 0

; #define LAS __attribute__((address_space(3)))
;     template <int M_> __device__ __forceinline__ f32x4 conv4(const f32x4 c4, const f32x4 pg, const LAS float* bp, int fr, const f32x4 w0, const f32x4 w1, const f32x4 w2, const f32x4 bsv, int db) const {
;         f32x4 p1, p2;
;         if (M_ > 0) {
; #pragma unroll
;             for (int e = 0; e < 4; ++e) { p1[e] = dpp_f<0x111>(dpp_r<0x121>(pg[e]), c4[e]); p2[e] = dpp_f<0x112>(dpp_r<0x122>(pg[e]), c4[e]); }
;         } else {
;             const f32x4 x1 = *(const LAS f32x4*)(bp + 256), x2 = *(const LAS f32x4*)(bp + (fr & 1) * 256);
; #pragma unroll
;             for (int e = 0; e < 4; ++e) { p1[e] = dpp_f<0x111>(x1[e], c4[e]); p2[e] = dpp_f<0x112>(x2[e], c4[e]); }
;         }
;         if ((unsigned)(db + 1) < 17u) { const int d = fr - db;
; #pragma unroll
;             for (int e = 0; e < 4; ++e) { p1[e] = d == 0 ? 0.f : p1[e]; p2[e] = (unsigned)d < 2u ? 0.f : p2[e]; } }
;         f32x4 uu = bsv + w2 * c4 + w1 * p1 + w0 * p2;
;         asm volatile("" : "+v"(uu));
;         return uu;
;     }
;     __device__ __forceinline__ void prompt(f32x4 (&acc)[2][2][4][2], const Unit& u, int row0t, int wr, int wc, int fr, int fq) const {
;     ...
;         for (int step = 0; step < 4; ++step) {
;             const int n = (step == 1 || step == 2) ? 1 : 0, ai = step >> 1;
;             f32x4 w0, w1, w2, bsv;
;             if (step != 2) { const unsigned cso = (unsigned)((DFF + ca + 4 * n) * 4);
;                 w0 = *(const f32x4*)((const char*)cw + cso); w1 = *(const f32x4*)((const char*)(cw + DFF2) + cso); w2 = *(const f32x4*)((const char*)(cw + 2 * DFF2) + cso); bsv = *(const f32x4*)((const char*)cb + cso);
;                 wk[0] = w0; wk[1] = w1; wk[2] = w2; wk[3] = bsv; }
;             else { w0 = wk[0]; w1 = wk[1]; w2 = wk[2]; bsv = wk[3]; }
;             int ps = ai * 2 + wr - 1; ps = ps < 0 ? 0 : ps;
;             const LAS float* bp = bnd + (ps * 2) * 256 + 128 + cl + 4 * n;
;             const int db0 = rho_b - (ai * HALF + wr * 64);
.LBB0_1275:
	v_pk_fma_f32 v[22:23], v[22:23], v[98:99], v[110:111]
	v_pk_fma_f32 v[20:21], v[20:21], v[96:97], v[108:109]
	v_pk_fma_f32 v[22:23], v[94:95], v[34:35], v[22:23]
	v_pk_fma_f32 v[20:21], v[92:93], v[32:33], v[20:21]
	v_lshl_add_u64 v[40:41], s[96:97], 0, v[18:19]
	v_lshl_add_u64 v[42:43], s[54:55], 0, v[18:19]
	v_lshl_add_u64 v[48:49], s[34:35], 0, v[18:19]
	v_lshl_add_u64 v[50:51], s[66:67], 0, v[18:19]
	v_pk_fma_f32 v[34:35], v[86:87], v[30:31], v[22:23]
	v_pk_fma_f32 v[32:33], v[84:85], v[28:29], v[20:21]
	s_nop 0
	global_load_dwordx4 v[20:23], v[40:41], off
	global_load_dwordx4 v[28:31], v[42:43], off
	s_nop 0
	global_load_dwordx4 v[40:43], v[48:49], off
	s_nop 0
	global_load_dwordx4 v[48:51], v[50:51], off
	v_mov_b32_dpp v78, v10 row_ror:1 row_mask:0xf bank_mask:0xf
	v_mov_b32_dpp v76, v10 row_ror:2 row_mask:0xf bank_mask:0xf
	v_mov_b32_dpp v79, v11 row_ror:1 row_mask:0xf bank_mask:0xf
	v_mov_b32_dpp v77, v11 row_ror:2 row_mask:0xf bank_mask:0xf
	v_mov_b32_dpp v86, v12 row_ror:1 row_mask:0xf bank_mask:0xf
	v_mov_b32_dpp v84, v12 row_ror:2 row_mask:0xf bank_mask:0xf
	v_mov_b32_dpp v87, v13 row_ror:1 row_mask:0xf bank_mask:0xf
	v_mov_b32_dpp v85, v13 row_ror:2 row_mask:0xf bank_mask:0xf
	v_mov_b32_dpp v78, v14 row_shr:1 row_mask:0xf bank_mask:0xf
	v_mov_b32_dpp v76, v14 row_shr:2 row_mask:0xf bank_mask:0xf
	v_mov_b32_dpp v79, v15 row_shr:1 row_mask:0xf bank_mask:0xf
	v_mov_b32_dpp v77, v15 row_shr:2 row_mask:0xf bank_mask:0xf
	v_mov_b32_dpp v86, v16 row_shr:1 row_mask:0xf bank_mask:0xf
	v_mov_b32_dpp v84, v16 row_shr:2 row_mask:0xf bank_mask:0xf
	v_mov_b32_dpp v87, v17 row_shr:1 row_mask:0xf bank_mask:0xf
	v_mov_b32_dpp v85, v17 row_shr:2 row_mask:0xf bank_mask:0xf
	s_and_b64 vcc, exec, s[12:13]
	s_mov_b64 s[0:1], -1
	s_cbranch_vccnz .LBB0_1277
	s_mov_b64 s[0:1], 0

; #define LAS __attribute__((address_space(3)))
;     template <int M_> __device__ __forceinline__ f32x4 conv4(const f32x4 c4, const f32x4 pg, const LAS float* bp, int fr, const f32x4 w0, const f32x4 w1, const f32x4 w2, const f32x4 bsv, int db) const {
;         f32x4 p1, p2;
;         if (M_ > 0) {
; #pragma unroll
;             for (int e = 0; e < 4; ++e) { p1[e] = dpp_f<0x111>(dpp_r<0x121>(pg[e]), c4[e]); p2[e] = dpp_f<0x112>(dpp_r<0x122>(pg[e]), c4[e]); }
;         } else {
;             const f32x4 x1 = *(const LAS f32x4*)(bp + 256), x2 = *(const LAS f32x4*)(bp + (fr & 1) * 256);
; #pragma unroll
;             for (int e = 0; e < 4; ++e) { p1[e] = dpp_f<0x111>(x1[e], c4[e]); p2[e] = dpp_f<0x112>(x2[e], c4[e]); }
;         }
;         if ((unsigned)(db + 1) < 17u) { const int d = fr - db;
; #pragma unroll
;             for (int e = 0; e < 4; ++e) { p1[e] = d == 0 ? 0.f : p1[e]; p2[e] = (unsigned)d < 2u ? 0.f : p2[e]; } }
;         f32x4 uu = bsv + w2 * c4 + w1 * p1 + w0 * p2;
;         asm volatile("" : "+v"(uu));
;         return uu;
;     }
;     __device__ __forceinline__ void prompt(f32x4 (&acc)[2][2][4][2], const Unit& u, int row0t, int wr, int wc, int fr, int fq) const {
;     ...
;             FFN_GATE_STORE(3); FFN_GATE_STORE(2); FFN_GATE_STORE(1); FFN_GATE_STORE(0);
.LBB0_1279:
	v_mul_f32_e32 v18, 0xbfb8aa3b, v102
	v_exp_f32_e32 v18, v18
	s_waitcnt vmcnt(0)
	v_pk_fma_f32 v[16:17], v[16:17], v[42:43], v[50:51]
	v_pk_fma_f32 v[14:15], v[14:15], v[40:41], v[48:49]
	v_pk_fma_f32 v[16:17], v[30:31], v[86:87], v[16:17]
	v_add_f32_e32 v18, 1.0, v18
	v_rcp_f32_e32 v90, v18
	v_mul_f32_e32 v18, 0xbfb8aa3b, v103
	v_exp_f32_e32 v18, v18
	v_pk_fma_f32 v[14:15], v[28:29], v[78:79], v[14:15]
	v_pk_fma_f32 v[16:17], v[22:23], v[84:85], v[16:17]
	v_pk_fma_f32 v[14:15], v[20:21], v[76:77], v[14:15]
	v_add_f32_e32 v18, 1.0, v18
	v_rcp_f32_e32 v91, v18
	v_mul_f32_e32 v18, 0xbfb8aa3b, v100
	v_exp_f32_e32 v18, v18
	v_pk_mul_f32 v[90:91], v[102:103], v[90:91]
	v_add_f32_e32 v18, 1.0, v18
	v_pk_mul_f32 v[70:71], v[90:91], v[70:71]
	v_rcp_f32_e32 v90, v18
	v_mul_f32_e32 v18, 0xbfb8aa3b, v101
	v_exp_f32_e32 v18, v18
	v_cvt_pk_bf16_f32 v71, v70, v71
	v_add_f32_e32 v18, 1.0, v18
	v_rcp_f32_e32 v91, v18
	v_mul_f32_e32 v18, 0xbfb8aa3b, v54
	v_exp_f32_e32 v18, v18
	v_pk_mul_f32 v[90:91], v[100:101], v[90:91]
	s_nop 0
	v_pk_mul_f32 v[68:69], v[90:91], v[68:69]
	v_add_f32_e32 v18, 1.0, v18
	v_cvt_pk_bf16_f32 v70, v68, v69
	v_rcp_f32_e32 v68, v18
	v_mul_f32_e32 v18, 0xbfb8aa3b, v55
	v_exp_f32_e32 v18, v18
	s_nop 0
	v_add_f32_e32 v18, 1.0, v18
	v_rcp_f32_e32 v69, v18
	s_nop 0
	v_pk_mul_f32 v[54:55], v[54:55], v[68:69]
	s_nop 0
	v_pk_mul_f32 v[16:17], v[54:55], v[16:17]
	s_nop 0
	v_cvt_pk_bf16_f32 v69, v16, v17
	v_mul_f32_e32 v16, 0xbfb8aa3b, v52
	v_mul_f32_e32 v17, 0xbfb8aa3b, v53
	v_exp_f32_e32 v16, v16
	v_exp_f32_e32 v17, v17
	v_add_f32_e32 v16, 1.0, v16
	v_add_f32_e32 v17, 1.0, v17
	v_rcp_f32_e32 v16, v16
	v_rcp_f32_e32 v17, v17
	s_nop 0
	v_pk_mul_f32 v[16:17], v[52:53], v[16:17]
	s_nop 0
	v_pk_mul_f32 v[14:15], v[16:17], v[14:15]
	s_nop 0
	v_cvt_pk_bf16_f32 v68, v14, v15
	v_add_u32_e32 v14, 0xb0000, v144
	global_store_dwordx4 v14, v[68:71], s[70:71]
	v_mov_b32_dpp v16, v6 row_ror:1 row_mask:0xf bank_mask:0xf
	v_mov_b32_dpp v14, v6 row_ror:2 row_mask:0xf bank_mask:0xf
	v_mov_b32_dpp v17, v7 row_ror:1 row_mask:0xf bank_mask:0xf
	v_mov_b32_dpp v15, v7 row_ror:2 row_mask:0xf bank_mask:0xf
	v_mov_b32_dpp v54, v8 row_ror:1 row_mask:0xf bank_mask:0xf
	v_mov_b32_dpp v52, v8 row_ror:2 row_mask:0xf bank_mask:0xf
	v_mov_b32_dpp v55, v9 row_ror:1 row_mask:0xf bank_mask:0xf
	v_mov_b32_dpp v53, v9 row_ror:2 row_mask:0xf bank_mask:0xf
	v_mov_b32_dpp v16, v10 row_shr:1 row_mask:0xf bank_mask:0xf
	v_mov_b32_dpp v14, v10 row_shr:2 row_mask:0xf bank_mask:0xf
	v_mov_b32_dpp v17, v11 row_shr:1 row_mask:0xf bank_mask:0xf
	v_mov_b32_dpp v15, v11 row_shr:2 row_mask:0xf bank_mask:0xf
	v_mov_b32_dpp v54, v12 row_shr:1 row_mask:0xf bank_mask:0xf
	v_mov_b32_dpp v52, v12 row_shr:2 row_mask:0xf bank_mask:0xf
	v_mov_b32_dpp v55, v13 row_shr:1 row_mask:0xf bank_mask:0xf
	v_mov_b32_dpp v53, v13 row_shr:2 row_mask:0xf bank_mask:0xf
	s_and_b64 vcc, exec, s[10:11]
	s_mov_b64 s[0:1], -1
	s_cbranch_vccnz .LBB0_1281
	s_mov_b64 s[0:1], 0

; #define LAS __attribute__((address_space(3)))
;     template <int M_> __device__ __forceinline__ f32x4 conv4(const f32x4 c4, const f32x4 pg, const LAS float* bp, int fr, const f32x4 w0, const f32x4 w1, const f32x4 w2, const f32x4 bsv, int db) const {
;         f32x4 p1, p2;
;         if (M_ > 0) {
; #pragma unroll
;             for (int e = 0; e < 4; ++e) { p1[e] = dpp_f<0x111>(dpp_r<0x121>(pg[e]), c4[e]); p2[e] = dpp_f<0x112>(dpp_r<0x122>(pg[e]), c4[e]); }
;         } else {
;             const f32x4 x1 = *(const LAS f32x4*)(bp + 256), x2 = *(const LAS f32x4*)(bp + (fr & 1) * 256);
; #pragma unroll
;             for (int e = 0; e < 4; ++e) { p1[e] = dpp_f<0x111>(x1[e], c4[e]); p2[e] = dpp_f<0x112>(x2[e], c4[e]); }
;         }
;         if ((unsigned)(db + 1) < 17u) { const int d = fr - db;
; #pragma unroll
;             for (int e = 0; e < 4; ++e) { p1[e] = d == 0 ? 0.f : p1[e]; p2[e] = (unsigned)d < 2u ? 0.f : p2[e]; } }
;         f32x4 uu = bsv + w2 * c4 + w1 * p1 + w0 * p2;
;         asm volatile("" : "+v"(uu));
;         return uu;
;     }
;     __device__ __forceinline__ void prompt(f32x4 (&acc)[2][2][4][2], const Unit& u, int row0t, int wr, int wc, int fr, int fq) const {
;     ...
;             FFN_GATE_STORE(3); FFN_GATE_STORE(2); FFN_GATE_STORE(1); FFN_GATE_STORE(0);
.LBB0_1283:
	v_mul_f32_e32 v18, 0xbfb8aa3b, v82
	v_exp_f32_e32 v18, v18
	v_pk_fma_f32 v[10:11], v[10:11], v[40:41], v[48:49]
	v_pk_fma_f32 v[12:13], v[12:13], v[42:43], v[50:51]
	v_pk_fma_f32 v[10:11], v[28:29], v[16:17], v[10:11]
	v_add_f32_e32 v18, 1.0, v18
	v_rcp_f32_e32 v68, v18
	v_mul_f32_e32 v18, 0xbfb8aa3b, v83
	v_exp_f32_e32 v18, v18
	v_pk_fma_f32 v[10:11], v[20:21], v[14:15], v[10:11]
	v_mul_f32_e32 v14, 0xbfb8aa3b, v46
	v_mul_f32_e32 v15, 0xbfb8aa3b, v47
	v_add_f32_e32 v18, 1.0, v18
	v_rcp_f32_e32 v69, v18
	v_mul_f32_e32 v18, 0xbfb8aa3b, v80
	v_exp_f32_e32 v18, v18
	v_exp_f32_e32 v14, v14
	v_pk_mul_f32 v[68:69], v[82:83], v[68:69]
	v_exp_f32_e32 v15, v15
	v_add_f32_e32 v18, 1.0, v18
	v_pk_mul_f32 v[62:63], v[68:69], v[62:63]
	v_rcp_f32_e32 v68, v18
	v_mul_f32_e32 v18, 0xbfb8aa3b, v81
	v_exp_f32_e32 v18, v18
	v_add_f32_e32 v14, 1.0, v14
	v_add_f32_e32 v15, 1.0, v15
	v_rcp_f32_e32 v14, v14
	v_add_f32_e32 v18, 1.0, v18
	v_rcp_f32_e32 v69, v18
	v_rcp_f32_e32 v15, v15
	v_pk_fma_f32 v[12:13], v[30:31], v[54:55], v[12:13]
	v_cvt_pk_bf16_f32 v63, v62, v63
	v_pk_fma_f32 v[12:13], v[22:23], v[52:53], v[12:13]
	v_pk_mul_f32 v[68:69], v[80:81], v[68:69]
	v_pk_mul_f32 v[14:15], v[46:47], v[14:15]
	v_pk_mul_f32 v[60:61], v[68:69], v[60:61]
	v_pk_mul_f32 v[12:13], v[14:15], v[12:13]
	v_cvt_pk_bf16_f32 v62, v60, v61
	v_cvt_pk_bf16_f32 v61, v12, v13
	v_mul_f32_e32 v12, 0xbfb8aa3b, v44
	v_mul_f32_e32 v13, 0xbfb8aa3b, v45
	v_exp_f32_e32 v12, v12
	v_exp_f32_e32 v13, v13
	v_add_f32_e32 v12, 1.0, v12
	v_add_f32_e32 v13, 1.0, v13
	v_rcp_f32_e32 v12, v12
	v_rcp_f32_e32 v13, v13
	s_nop 0
	v_pk_mul_f32 v[12:13], v[44:45], v[12:13]
	s_nop 0
	v_pk_mul_f32 v[10:11], v[12:13], v[10:11]
	s_nop 0
	v_cvt_pk_bf16_f32 v60, v10, v11
	v_add_u32_e32 v10, 0xb0000, v104
	global_store_dwordx4 v10, v[60:63], s[70:71]
	v_mov_b32_dpp v12, v2 row_ror:1 row_mask:0xf bank_mask:0xf
	v_mov_b32_dpp v10, v2 row_ror:2 row_mask:0xf bank_mask:0xf
	v_mov_b32_dpp v13, v3 row_ror:1 row_mask:0xf bank_mask:0xf
	v_mov_b32_dpp v11, v3 row_ror:2 row_mask:0xf bank_mask:0xf
	v_mov_b32_dpp v16, v4 row_ror:1 row_mask:0xf bank_mask:0xf
	v_mov_b32_dpp v14, v4 row_ror:2 row_mask:0xf bank_mask:0xf
	v_mov_b32_dpp v17, v5 row_ror:1 row_mask:0xf bank_mask:0xf
	v_mov_b32_dpp v15, v5 row_ror:2 row_mask:0xf bank_mask:0xf
	v_mov_b32_dpp v12, v6 row_shr:1 row_mask:0xf bank_mask:0xf
	v_mov_b32_dpp v10, v6 row_shr:2 row_mask:0xf bank_mask:0xf
	v_mov_b32_dpp v13, v7 row_shr:1 row_mask:0xf bank_mask:0xf
	v_mov_b32_dpp v11, v7 row_shr:2 row_mask:0xf bank_mask:0xf
	v_mov_b32_dpp v16, v8 row_shr:1 row_mask:0xf bank_mask:0xf
	v_mov_b32_dpp v14, v8 row_shr:2 row_mask:0xf bank_mask:0xf
	v_mov_b32_dpp v17, v9 row_shr:1 row_mask:0xf bank_mask:0xf
	v_mov_b32_dpp v15, v9 row_shr:2 row_mask:0xf bank_mask:0xf
	s_and_b64 vcc, exec, s[8:9]
	s_mov_b64 s[0:1], -1
	s_cbranch_vccnz .LBB0_1285
	s_mov_b64 s[0:1], 0
